# physical XCC block ids; conv chunks and attention heads placed on the XCD that produced their rows; seams 2,5,6 synchronise one XCD only; late rescale test with exact redo in attention
# speedup vs baseline: 1.0333x; 1.0156x over previous
_Z8yoco_fwd4Args:
	s_load_dwordx8 s[56:63], s[0:1], 0x80
	s_mov_b32 s33, s2
	s_add_u32 s2, s0, 0xa0
	s_addc_u32 s3, s1, 0
	s_load_dwordx2 s[64:65], s[0:1], 0xa0
	s_waitcnt lgkmcnt(0)
	s_add_u32 s4, s60, 0x1400000
	s_addc_u32 s5, s61, 0
	v_and_b32_e32 v207, 0x3ff, v0
	v_writelane_b32 v243, s4, 0
	v_readfirstlane_b32 s38, v207
	v_cmp_eq_u32_e64 s[6:7], 0, v207
	v_writelane_b32 v243, s5, 1
	s_getreg_b32 s4, hwreg(HW_REG_XCC_ID, 0, 4)
	s_and_b32 s4, s4, 15
	v_writelane_b32 v243, s4, 2
	s_mov_b64 s[4:5], exec
	v_writelane_b32 v243, s6, 3
	s_nop 1
	v_writelane_b32 v243, s7, 4
	s_and_b64 s[6:7], s[4:5], s[6:7]
	s_mov_b64 exec, s[6:7]
	s_cbranch_execz .LBB0_17
	s_load_dword s10, s[0:1], 0xa8
	s_mov_b64 s[8:9], exec
	v_mbcnt_lo_u32_b32 v1, s8, 0
	v_mbcnt_hi_u32_b32 v1, s9, v1
	v_cmp_eq_u32_e32 vcc, 0, v1
	s_and_saveexec_b64 s[6:7], vcc
	s_cbranch_execz .LBB0_3
	v_readlane_b32 s11, v243, 2
	s_bcnt1_i32_b64 s8, s[8:9]
	s_lshl_b32 s11, s11, 8
	v_mov_b32_e32 v2, s8
	v_readlane_b32 s8, v243, 0
	v_mov_b32_e32 v1, s11
	v_readlane_b32 s9, v243, 1
	s_nop 4
	global_atomic_add v19, v1, v2, s[8:9] offset:1024 sc0

.LBB0_16:
	v_max_u32_e32 v20, v16, v1
	v_max_u32_e32 v20, v20, v2
	v_max_u32_e32 v20, v20, v3
	v_max_u32_e32 v20, v20, v4
	v_max_u32_e32 v20, v20, v5
	v_max_u32_e32 v20, v20, v6
	v_max_u32_e32 v20, v20, v7
	v_max_u32_e32 v20, v20, v8
	v_max_u32_e32 v20, v20, v9
	v_max_u32_e32 v20, v20, v10
	v_max_u32_e32 v20, v20, v11
	v_max_u32_e32 v20, v20, v12
	v_max_u32_e32 v20, v20, v13
	v_max_u32_e32 v20, v20, v14
	v_max_u32_e32 v20, v20, v15
	v_readlane_b32 s6, v243, 2
	s_cmp_eq_u32 s6, 0
	s_cselect_b64 vcc, -1, 0
	s_cmp_eq_u32 s6, 1
	v_cndmask_b32_e32 v17, 0, v16, vcc
	s_cselect_b64 vcc, -1, 0
	s_cmp_eq_u32 s6, 2
	v_cndmask_b32_e32 v17, v17, v1, vcc
	s_cselect_b64 vcc, -1, 0
	s_cmp_eq_u32 s6, 3
	v_cndmask_b32_e32 v17, v17, v2, vcc
	s_cselect_b64 vcc, -1, 0
	s_cmp_eq_u32 s6, 4
	v_cndmask_b32_e32 v17, v17, v3, vcc
	s_cselect_b64 vcc, -1, 0
	s_cmp_eq_u32 s6, 5
	v_cndmask_b32_e32 v17, v17, v4, vcc
	s_cselect_b64 vcc, -1, 0
	s_cmp_eq_u32 s6, 6
	v_cndmask_b32_e32 v17, v17, v5, vcc
	s_cselect_b64 vcc, -1, 0
	s_cmp_eq_u32 s6, 7
	v_cndmask_b32_e32 v17, v17, v6, vcc
	s_cselect_b64 vcc, -1, 0
	s_cmp_eq_u32 s6, 8
	v_cndmask_b32_e32 v17, v17, v7, vcc
	s_cselect_b64 vcc, -1, 0
	s_cmp_eq_u32 s6, 9
	v_cndmask_b32_e32 v17, v17, v8, vcc
	s_cselect_b64 vcc, -1, 0
	s_cmp_eq_u32 s6, 10
	v_cndmask_b32_e32 v17, v17, v9, vcc
	s_cselect_b64 vcc, -1, 0
	s_cmp_eq_u32 s6, 11
	v_cndmask_b32_e32 v17, v17, v10, vcc
	s_cselect_b64 vcc, -1, 0
	s_cmp_eq_u32 s6, 12
	v_cndmask_b32_e32 v17, v17, v11, vcc
	s_cselect_b64 vcc, -1, 0
	s_cmp_eq_u32 s6, 13
	v_cndmask_b32_e32 v17, v17, v12, vcc
	s_cselect_b64 vcc, -1, 0
	s_cmp_eq_u32 s6, 14
	v_cndmask_b32_e32 v17, v17, v13, vcc
	s_cselect_b64 vcc, -1, 0
	s_cmp_eq_u32 s6, 15
	v_cndmask_b32_e32 v17, v17, v14, vcc
	s_cselect_b64 vcc, -1, 0
	v_cndmask_b32_e32 v17, v17, v15, vcc
	v_cmp_ne_u32_e32 vcc, 0, v16
	s_nop 1
	v_cndmask_b32_e64 v16, 0, 1, vcc
	v_cmp_ne_u32_e32 vcc, 0, v1
	s_nop 1
	v_addc_co_u32_e32 v1, vcc, 0, v16, vcc
	v_cmp_ne_u32_e32 vcc, 0, v2
	s_nop 1
	v_cndmask_b32_e64 v2, 0, 1, vcc
	v_cmp_ne_u32_e32 vcc, 0, v3
	v_mov_b32_e32 v3, 0
	s_nop 0
	v_addc_co_u32_e32 v1, vcc, v1, v2, vcc
	v_cmp_ne_u32_e32 vcc, 0, v4
	s_nop 1
	v_cndmask_b32_e64 v2, 0, 1, vcc
	v_cmp_ne_u32_e32 vcc, 0, v5
	s_nop 1
	v_addc_co_u32_e32 v1, vcc, v1, v2, vcc
	v_cmp_ne_u32_e32 vcc, 0, v6
	s_nop 1
	v_cndmask_b32_e64 v2, 0, 1, vcc
	v_cmp_ne_u32_e32 vcc, 0, v7
	s_nop 1
	v_addc_co_u32_e32 v1, vcc, v1, v2, vcc
	v_cmp_ne_u32_e32 vcc, 0, v8
	s_nop 1
	v_cndmask_b32_e64 v2, 0, 1, vcc
	v_cmp_ne_u32_e32 vcc, 0, v9
	s_nop 1
	v_addc_co_u32_e32 v1, vcc, v1, v2, vcc
	v_cmp_ne_u32_e32 vcc, 0, v10
	s_nop 1
	v_cndmask_b32_e64 v2, 0, 1, vcc
	v_cmp_ne_u32_e32 vcc, 0, v11
	s_nop 1
	v_addc_co_u32_e32 v1, vcc, v1, v2, vcc
	v_cmp_ne_u32_e32 vcc, 0, v12
	s_nop 1
	v_cndmask_b32_e64 v2, 0, 1, vcc
	v_cmp_ne_u32_e32 vcc, 0, v13
	s_nop 1
	v_addc_co_u32_e32 v1, vcc, v1, v2, vcc
	v_cmp_ne_u32_e32 vcc, 0, v14
	s_nop 1
	v_cndmask_b32_e64 v2, 0, 1, vcc
	v_cmp_ne_u32_e32 vcc, 0, v15
	s_nop 1
	v_addc_co_u32_e32 v1, vcc, v1, v2, vcc
	v_max_u32_e32 v2, 1, v17
	v_max_u32_e32 v1, 1, v1
	ds_write_b32 v3, v2
	ds_write_b32 v3, v1 offset:4
	v_cmp_eq_u32_e32 vcc, 32, v20
	s_nop 1
	v_cndmask_b32_e64 v21, 0, 1, vcc
	v_cmp_eq_u32_e32 vcc, 8, v1
	s_nop 1
	v_cndmask_b32_e64 v22, 0, 1, vcc
	v_and_b32_e32 v21, v21, v22
	v_lshl_add_u32 v22, v19, 3, s6
	v_mov_b32_e32 v23, s33
	v_cmp_ne_u32_e32 vcc, 0, v21
	s_nop 1
	v_cndmask_b32_e32 v22, v23, v22, vcc
	ds_write_b32 v3, v22 offset:8
	ds_write_b32 v3, v21 offset:12
.LBB0_17:
	s_or_b64 exec, exec, s[4:5]
	v_mov_b32_e32 v1, 0
	s_load_dwordx16 s[8:23], s[0:1], 0x0
	s_load_dwordx16 s[40:55], s[0:1], 0x40
	s_waitcnt lgkmcnt(0)
	s_barrier
	ds_read_b32 v2, v1
	ds_read_b32 v20, v1 offset:8
	ds_read_b32 v21, v1 offset:12
	ds_read_b32 v1, v1 offset:4
	s_cmp_le_i32 s62, s63
	s_waitcnt lgkmcnt(0)
	s_barrier
	v_readfirstlane_b32 s33, v20
	v_readfirstlane_b32 s101, v21
	v_readfirstlane_b32 s80, v2
	v_readfirstlane_b32 s0, v1
	s_nop 1
	v_writelane_b32 v243, s0, 5
	s_cbranch_scc1 .LBB0_29
	v_lshrrev_b32_e32 v1, 20, v0
	v_lshrrev_b32_e32 v0, 10, v0
	v_or_b32_e32 v0, v0, v1
	s_movk_i32 s0, 0x3ff
	v_and_or_b32 v0, v0, s0, v207
	v_cmp_eq_u32_e32 vcc, 0, v0
	s_barrier
	s_and_saveexec_b64 s[0:1], vcc
	s_cbranch_execz .LBB0_28
	buffer_wbl2 sc1
	s_waitcnt vmcnt(0)
	s_load_dwordx2 s[2:3], s[2:3], 0x58
	v_mov_b32_e32 v2, 0
	s_mov_b64 s[4:5], exec
	v_mbcnt_lo_u32_b32 v1, s4, 0
	v_mbcnt_hi_u32_b32 v1, s5, v1
	s_waitcnt lgkmcnt(0)
	global_load_dword v0, v2, s[2:3] offset:40
	v_cmp_eq_u32_e32 vcc, 0, v1
	s_and_saveexec_b64 s[6:7], vcc
	s_cbranch_execz .LBB0_21
	s_bcnt1_i32_b64 s4, s[4:5]
	v_mov_b32_e32 v3, s4
	global_atomic_add v3, v2, v3, s[2:3] offset:32 sc0

.LBB0_448:
	s_cmp_lt_i32 s62, 3
	s_cselect_b64 s[4:5], -1, 0
	s_add_u32 s44, s60, 0x16000000
	s_addc_u32 s45, s61, 0
	s_and_b64 s[22:23], s[4:5], s[2:3]
	s_andn2_b64 vcc, exec, s[22:23]
	s_cbranch_vccnz .LBB0_468
	s_cmpk_gt_i32 s33, 0xff
	s_cbranch_scc1 .LBB0_468
	v_lshlrev_b32_e32 v0, 3, v207
	v_mov_b32_e32 v1, 0
	v_and_b32_e32 v6, 32, v207
	v_lshl_add_u64 v[2:3], s[14:15], 0, v[0:1]
	v_cmp_eq_u32_e64 s[2:3], 0, v6
	v_and_b32_e32 v6, 16, v207
	s_movk_i32 s6, 0x2000
	v_cmp_eq_u32_e64 s[4:5], 0, v6
	v_add_co_u32_e32 v6, vcc, s6, v2
	s_movk_i32 s6, 0x4000
	s_nop 0
	v_addc_co_u32_e32 v7, vcc, 0, v3, vcc
	v_add_co_u32_e32 v8, vcc, s6, v2
	s_movk_i32 s6, 0x6000
	s_nop 0
	v_addc_co_u32_e32 v9, vcc, 0, v3, vcc
	global_load_dwordx2 v[38:39], v[6:7], off offset:-4096
	global_load_dwordx2 v[40:41], v[6:7], off
	global_load_dwordx2 v[42:43], v[8:9], off offset:-4096
	global_load_dwordx2 v[44:45], v[8:9], off
	v_add_co_u32_e32 v6, vcc, s6, v2
	s_mov_b32 s6, 0x8000
	s_nop 0
	v_addc_co_u32_e32 v7, vcc, 0, v3, vcc
	v_add_co_u32_e32 v8, vcc, s6, v2
	s_mov_b32 s6, 0xa000
	s_nop 0
	v_addc_co_u32_e32 v9, vcc, 0, v3, vcc
	global_load_dwordx2 v[46:47], v[6:7], off offset:-4096
	global_load_dwordx2 v[48:49], v[6:7], off
	global_load_dwordx2 v[50:51], v[8:9], off offset:-4096
	global_load_dwordx2 v[52:53], v[8:9], off
	v_add_co_u32_e32 v6, vcc, s6, v2
	s_mov_b32 s6, 0xc000
	s_nop 0
	v_addc_co_u32_e32 v7, vcc, 0, v3, vcc
	v_add_co_u32_e32 v8, vcc, s6, v2
	s_mov_b32 s6, 0xe000
	s_nop 0
	v_addc_co_u32_e32 v9, vcc, 0, v3, vcc
	global_load_dwordx2 v[54:55], v[6:7], off offset:-4096
	global_load_dwordx2 v[56:57], v[6:7], off
	global_load_dwordx2 v[58:59], v[8:9], off offset:-4096
	global_load_dwordx2 v[60:61], v[8:9], off
	v_add_co_u32_e32 v6, vcc, s6, v2
	s_mov_b32 s6, 0x10000
	s_nop 0
	v_addc_co_u32_e32 v7, vcc, 0, v3, vcc
	v_add_co_u32_e32 v8, vcc, s6, v2
	s_mov_b32 s6, 0x12000
	s_nop 0
	v_addc_co_u32_e32 v9, vcc, 0, v3, vcc
	global_load_dwordx2 v[62:63], v[6:7], off offset:-4096
	global_load_dwordx2 v[64:65], v[6:7], off
	global_load_dwordx2 v[66:67], v[8:9], off offset:-4096
	global_load_dwordx2 v[68:69], v[8:9], off
	v_add_co_u32_e32 v6, vcc, s6, v2
	s_mov_b32 s6, 0x14000
	s_nop 0
	v_addc_co_u32_e32 v7, vcc, 0, v3, vcc
	v_add_co_u32_e32 v8, vcc, s6, v2
	s_mov_b32 s6, 0x16000
	s_nop 0
	v_addc_co_u32_e32 v9, vcc, 0, v3, vcc
	global_load_dwordx2 v[70:71], v[6:7], off offset:-4096
	global_load_dwordx2 v[72:73], v[6:7], off
	global_load_dwordx2 v[74:75], v[8:9], off offset:-4096
	global_load_dwordx2 v[76:77], v[8:9], off
	v_add_co_u32_e32 v6, vcc, s6, v2
	s_mov_b32 s6, 0x18000
	s_nop 0
	v_addc_co_u32_e32 v7, vcc, 0, v3, vcc
	v_add_co_u32_e32 v8, vcc, s6, v2
	s_mov_b32 s6, 0x1a000
	s_nop 0
	v_addc_co_u32_e32 v9, vcc, 0, v3, vcc
	global_load_dwordx2 v[78:79], v[6:7], off offset:-4096
	global_load_dwordx2 v[80:81], v[6:7], off
	global_load_dwordx2 v[82:83], v[8:9], off offset:-4096
	global_load_dwordx2 v[84:85], v[8:9], off
	v_add_co_u32_e32 v6, vcc, s6, v2
	s_mov_b32 s6, 0x1c000
	s_nop 0
	v_addc_co_u32_e32 v7, vcc, 0, v3, vcc
	v_add_co_u32_e32 v8, vcc, s6, v2
	s_mov_b32 s6, 0x1e000
	s_nop 0
	v_addc_co_u32_e32 v9, vcc, 0, v3, vcc
	v_add_co_u32_e32 v2, vcc, s6, v2
	global_load_dwordx2 v[86:87], v[6:7], off offset:-4096
	global_load_dwordx2 v[88:89], v[6:7], off
	global_load_dwordx2 v[90:91], v[8:9], off offset:-4096
	global_load_dwordx2 v[92:93], v[8:9], off
	v_addc_co_u32_e32 v3, vcc, 0, v3, vcc
	global_load_dwordx2 v[94:95], v[2:3], off offset:-4096
	global_load_dwordx2 v[96:97], v[2:3], off
	global_load_dwordx2 v[98:99], v0, s[14:15]
	global_load_dwordx2 v[100:101], v0, s[16:17]
	global_load_dwordx2 v[102:103], v0, s[20:21]
	global_load_dwordx2 v[104:105], v0, s[18:19]
	v_and_b32_e32 v2, 8, v207
	v_cmp_eq_u32_e64 s[6:7], 0, v2
	v_and_b32_e32 v2, 4, v207
	v_cmp_eq_u32_e64 s[8:9], 0, v2
	v_and_b32_e32 v2, 3, v207
	s_add_i32 s14, 0, 0x20000
	s_add_i32 s15, 0, 0x20200
	v_cmp_eq_u32_e64 s[10:11], 0, v2
	v_and_b32_e32 v2, 0x3c0, v207
	v_and_b32_e32 v3, 60, v207
	v_add_u32_e32 v186, s14, v0
	v_add_u32_e32 v187, s15, v0
	v_lshlrev_b32_e32 v0, 4, v207
	v_add3_u32 v185, s14, v2, v3
	v_and_b32_e32 v2, 0x7f0, v0
	v_and_b32_e32 v0, 0x7f, v207
	v_lshlrev_b32_e32 v0, 4, v0
	v_mov_b32_e32 v5, v1
	v_mov_b32_e32 v3, v1
	v_lshl_add_u64 v[110:111], s[42:43], 0, v[0:1]
	v_add_u32_e32 v1, 0x200, v207
	v_lshrrev_b32_e32 v190, 7, v1
	v_add_u32_e32 v1, 0x600, v207
	v_lshrrev_b32_e32 v192, 7, v1
	v_add_u32_e32 v1, 0xa00, v207
	v_lshrrev_b32_e32 v194, 7, v1
	v_add_u32_e32 v1, 0xe00, v207
	v_lshrrev_b32_e32 v196, 7, v1
	v_mbcnt_lo_u32_b32 v1, -1, 0
	v_mbcnt_hi_u32_b32 v1, -1, v1
	v_lshl_add_u64 v[108:109], s[42:43], 0, v[2:3]
	v_and_b32_e32 v3, 64, v1
	v_add_u32_e32 v188, 0, v2
	v_xor_b32_e32 v2, 32, v1
	v_add_u32_e32 v3, 64, v3
	v_cmp_lt_i32_e32 vcc, v2, v3
	v_lshlrev_b32_e32 v4, 2, v207
	v_lshrrev_b32_e32 v189, 7, v207
	v_cndmask_b32_e32 v2, v1, v2, vcc
	v_lshlrev_b32_e32 v197, 2, v2
	v_xor_b32_e32 v2, 16, v1
	v_cmp_lt_i32_e32 vcc, v2, v3
	v_add_u32_e32 v184, 0, v4
	s_and_b32 s100, s33, 7
	s_lshl_b32 s100, s100, 5
	s_lshr_b32 s99, s33, 3
	s_add_i32 s100, s100, s99
	s_lshl_b32 s14, s100, 7
	v_cndmask_b32_e32 v2, v1, v2, vcc
	v_lshlrev_b32_e32 v198, 2, v2
	v_xor_b32_e32 v2, 8, v1
	v_cmp_lt_i32_e32 vcc, v2, v3
	v_lshl_or_b32 v0, v189, 11, v0
	v_lshl_add_u64 v[36:37], s[0:1], 0, v[4:5]
	v_cndmask_b32_e32 v2, v1, v2, vcc
	v_lshlrev_b32_e32 v199, 2, v2
	v_xor_b32_e32 v2, 4, v1
	v_cmp_lt_i32_e32 vcc, v2, v3
	v_cmp_gt_u32_e64 s[12:13], 8, v207
	v_lshl_add_u64 v[106:107], s[44:45], 0, v[4:5]
	v_cndmask_b32_e32 v2, v1, v2, vcc
	v_lshlrev_b32_e32 v200, 2, v2
	v_xor_b32_e32 v2, 2, v1
	v_cmp_lt_i32_e32 vcc, v2, v3
	v_or_b32_e32 v191, 8, v189
	v_or_b32_e32 v193, 16, v189
	v_cndmask_b32_e32 v2, v1, v2, vcc
	v_lshlrev_b32_e32 v201, 2, v2
	v_xor_b32_e32 v2, 1, v1
	v_cmp_lt_i32_e32 vcc, v2, v3
	v_or_b32_e32 v195, 24, v189
	v_add_u32_e32 v203, 0xfffffe00, v207
	v_cndmask_b32_e32 v1, v1, v2, vcc
	v_lshlrev_b32_e32 v202, 2, v1
	s_sub_i32 s38, s14, 30
	s_lshl_b32 s39, s64, 7
	v_add_u32_e32 v204, 0, v0
	s_or_b32 s54, s14, 7
	v_add_u32_e32 v205, 0x800, v184
	s_movk_i32 s55, 0x1cff
	s_mov_b32 s14, 0x3a800000
	s_mov_b32 s65, 0x800000
	s_add_i32 s66, 0, 0x20210
	s_add_i32 s67, 0, 0x20220
	s_add_i32 s70, 0, 0x20230
	s_mov_b32 s71, s100
	s_branch .LBB0_452

.LBB0_486:
	s_andn2_saveexec_b64 s[8:9], s[8:9]
	s_cbranch_execz .LBB0_506
	s_mov_b64 s[8:9], exec
	s_cmp_eq_u32 s101, 0
	s_cbranch_scc0 .LBB0_503
	buffer_wbl2 sc1
	s_waitcnt vmcnt(0)
	v_mbcnt_lo_u32_b32 v0, s8, 0
	v_mbcnt_hi_u32_b32 v0, s9, v0
	v_cmp_eq_u32_e32 vcc, 0, v0
	s_and_saveexec_b64 s[10:11], vcc
	s_cbranch_execz .LBB0_489
	s_bcnt1_i32_b64 s8, s[8:9]
	v_mov_b32_e32 v1, 0x1403000
	v_mov_b32_e32 v2, s8
	global_atomic_add v1, v1, v2, s[60:61] offset:1024 sc0

.LBB0_732:
	s_cmp_lt_i32 s62, 7
	s_cselect_b64 s[4:5], -1, 0
	s_and_b64 s[2:3], s[4:5], s[2:3]
	s_andn2_b64 vcc, exec, s[2:3]
	s_cbranch_vccnz .LBB0_810
	v_lshlrev_b32_e32 v0, 2, v206
	global_load_dword v1, v0, s[50:51]
	global_load_dword v2, v0, s[50:51] offset:256
	global_load_dword v3, v0, s[50:51] offset:512
	global_load_dword v4, v0, s[50:51] offset:768
	v_mbcnt_lo_u32_b32 v0, -1, 0
	v_mbcnt_hi_u32_b32 v0, -1, v0
	v_and_b32_e32 v5, 64, v0
	v_xor_b32_e32 v6, 1, v0
	v_add_u32_e32 v5, 64, v5
	v_cmp_lt_i32_e32 vcc, v6, v5
	v_xor_b32_e32 v7, 2, v0
	v_xor_b32_e32 v8, 4, v0
	v_cndmask_b32_e32 v6, v0, v6, vcc
	v_lshlrev_b32_e32 v6, 2, v6
	v_cmp_lt_i32_e32 vcc, v7, v5
	v_xor_b32_e32 v9, 8, v0
	v_xor_b32_e32 v10, 16, v0
	v_cndmask_b32_e32 v7, v0, v7, vcc
	v_lshlrev_b32_e32 v7, 2, v7
	v_cmp_lt_i32_e32 vcc, v8, v5
	v_xor_b32_e32 v11, 32, v0
	s_cmpk_gt_i32 s33, 0xff
	s_mov_b32 s47, 0
	s_waitcnt vmcnt(0)
	v_mul_f32_e32 v12, v1, v2
	ds_bpermute_b32 v12, v6, v12
	v_mul_f32_e32 v13, v3, v4
	ds_bpermute_b32 v6, v6, v13
	s_waitcnt lgkmcnt(1)
	v_fmac_f32_e32 v12, v1, v2
	ds_bpermute_b32 v1, v7, v12
	s_waitcnt lgkmcnt(1)
	v_fmac_f32_e32 v6, v3, v4
	ds_bpermute_b32 v2, v7, v6
	v_cndmask_b32_e32 v3, v0, v8, vcc
	v_lshlrev_b32_e32 v3, 2, v3
	s_waitcnt lgkmcnt(1)
	v_add_f32_e32 v1, v12, v1
	ds_bpermute_b32 v4, v3, v1
	s_waitcnt lgkmcnt(1)
	v_add_f32_e32 v2, v6, v2
	ds_bpermute_b32 v3, v3, v2
	v_cmp_lt_i32_e32 vcc, v9, v5
	s_waitcnt lgkmcnt(1)
	v_add_f32_e32 v1, v1, v4
	v_cndmask_b32_e32 v6, v0, v9, vcc
	v_lshlrev_b32_e32 v6, 2, v6
	s_waitcnt lgkmcnt(0)
	v_add_f32_e32 v2, v2, v3
	ds_bpermute_b32 v3, v6, v1
	ds_bpermute_b32 v4, v6, v2
	v_cmp_lt_i32_e32 vcc, v10, v5
	s_waitcnt lgkmcnt(1)
	v_add_f32_e32 v1, v1, v3
	v_cndmask_b32_e32 v6, v0, v10, vcc
	v_lshlrev_b32_e32 v6, 2, v6
	s_waitcnt lgkmcnt(0)
	v_add_f32_e32 v3, v2, v4
	ds_bpermute_b32 v2, v6, v1
	ds_bpermute_b32 v4, v6, v3
	v_cmp_lt_i32_e32 vcc, v11, v5
	s_waitcnt lgkmcnt(1)
	v_add_f32_e32 v2, v1, v2
	v_cndmask_b32_e32 v0, v0, v11, vcc
	v_lshlrev_b32_e32 v5, 2, v0
	s_waitcnt lgkmcnt(0)
	v_add_f32_e32 v0, v3, v4
	ds_bpermute_b32 v3, v5, v2
	ds_bpermute_b32 v1, v5, v0
	s_cbranch_scc1 .LBB0_810
	v_writelane_b32 v243, s2, 7
	s_waitcnt lgkmcnt(1)
	v_add_f32_e32 v2, v2, v3
	v_mul_f32_e32 v3, 0x3fb8aa3b, v2
	v_writelane_b32 v243, s3, 8
	s_mov_b32 s2, 0x3fb8aa3b
	v_fma_f32 v4, v2, s2, -v3
	v_rndne_f32_e32 v5, v3
	v_fmac_f32_e32 v4, 0x32a5705f, v2
	v_sub_f32_e32 v3, v3, v5
	v_add_f32_e32 v3, v3, v4
	v_exp_f32_e32 v3, v3
	v_cvt_i32_f32_e32 v4, v5
	s_waitcnt lgkmcnt(0)
	v_add_f32_e32 v0, v0, v1
	s_mov_b32 s3, 0xc2ce8ed0
	v_cmp_ngt_f32_e32 vcc, s3, v2
	v_ldexp_f32 v1, v3, v4
	v_mul_f32_e32 v3, 0x3fb8aa3b, v0
	v_fma_f32 v4, v0, s2, -v3
	v_rndne_f32_e32 v5, v3
	v_fmac_f32_e32 v4, 0x32a5705f, v0
	v_sub_f32_e32 v3, v3, v5
	v_add_f32_e32 v3, v3, v4
	v_exp_f32_e32 v3, v3
	v_cvt_i32_f32_e32 v4, v5
	s_mov_b32 s4, 0x42b17218
	v_cndmask_b32_e32 v1, 0, v1, vcc
	v_mov_b32_e32 v5, 0x7f800000
	v_cmp_nlt_f32_e32 vcc, s4, v2
	v_ldexp_f32 v2, v3, v4
	v_lshrrev_b32_e32 v3, 1, v207
	v_cndmask_b32_e32 v1, v5, v1, vcc
	v_cmp_ngt_f32_e32 vcc, s3, v0
	v_and_b32_e32 v3, 4, v3
	v_lshrrev_b32_e32 v210, 5, v206
	v_cndmask_b32_e32 v2, 0, v2, vcc
	v_cmp_nlt_f32_e32 vcc, s4, v0
	v_lshlrev_b32_e32 v176, 4, v210
	v_mov_b32_e32 v177, 0
	v_cndmask_b32_e32 v0, v5, v2, vcc
	v_lshlrev_b32_e32 v2, 1, v207
	v_sub_f32_e32 v0, v1, v0
	v_and_b32_e32 v1, 19, v207
	v_and_b32_e32 v2, 8, v2
	v_or3_b32 v1, v2, v1, v3
	v_lshlrev_b32_e32 v2, 8, v1
	v_bitop3_b32 v1, v1, v210, 15 bitop3:0x6c
	v_lshl_add_u64 v[178:179], s[0:1], 0, v[176:177]
	v_lshlrev_b32_e32 v1, 4, v1
	s_movk_i32 s0, 0x60
	v_bitop3_b32 v6, v1, s0, v2 bitop3:0x36
	s_movk_i32 s0, 0x80
	v_bitop3_b32 v7, v1, s0, v2 bitop3:0x36
	s_movk_i32 s0, 0xa0
	v_bitop3_b32 v8, v1, s0, v2 bitop3:0x36
	s_movk_i32 s0, 0xc0
	v_bitop3_b32 v9, v1, s0, v2 bitop3:0x36
	s_movk_i32 s0, 0xe0
	v_add_f32_e32 v208, 0x3ef1014c, v0
	v_lshlrev_b32_e32 v0, 3, v210
	v_or_b32_e32 v3, v1, v2
	v_bitop3_b32 v4, v1, 32, v2 bitop3:0x36
	v_bitop3_b32 v5, v1, 64, v2 bitop3:0x36
	v_bitop3_b32 v1, v1, s0, v2 bitop3:0x36
	v_bfe_u32 v2, v207, 2, 2
	v_lshrrev_b32_e32 v13, 3, v207
	v_bfe_u32 v14, v207, 1, 1
	v_or_b32_e32 v10, v0, v2
	v_lshlrev_b32_e32 v2, 2, v2
	v_lshlrev_b32_e32 v11, 1, v210
	v_and_or_b32 v13, v13, 2, v14
	v_lshlrev_b32_e32 v14, 3, v207
	v_bitop3_b32 v15, v11, v13, v2 bitop3:0x36
	v_or_b32_e32 v12, v11, v2
	v_and_b32_e32 v14, 8, v14
	v_lshl_add_u32 v10, v10, 8, 0
	v_lshlrev_b32_e32 v15, 4, v15
	v_add3_u32 v215, v10, v15, v14
	v_bitop3_b32 v15, v12, v13, 1 bitop3:0x36
	v_lshlrev_b32_e32 v15, 4, v15
	v_add3_u32 v217, v10, v15, v14
	v_or_b32_e32 v15, 4, v13
	v_bitop3_b32 v16, v11, v15, v2 bitop3:0x36
	v_bitop3_b32 v15, v12, v15, 1 bitop3:0x36
	v_lshlrev_b32_e32 v15, 4, v15
	v_lshlrev_b32_e32 v16, 4, v16
	v_add3_u32 v221, v10, v15, v14
	v_or_b32_e32 v15, 8, v13
	v_or_b32_e32 v13, 12, v13
	v_add3_u32 v219, v10, v16, v14
	v_bitop3_b32 v16, v11, v15, v2 bitop3:0x36
	v_bitop3_b32 v2, v11, v13, v2 bitop3:0x36
	v_lshlrev_b32_e32 v2, 4, v2
	v_add3_u32 v227, v10, v2, v14
	v_bitop3_b32 v2, v12, v13, 1 bitop3:0x36
	v_lshlrev_b32_e32 v2, 4, v2
	v_and_b32_e32 v209, 31, v207
	v_add3_u32 v229, v10, v2, v14
	v_or_b32_e32 v2, 2, v0
	v_cmp_gt_u32_e64 s[6:7], v2, v209
	v_or_b32_e32 v2, 3, v0
	v_cmp_gt_u32_e64 s[8:9], v2, v209
	v_or_b32_e32 v2, 4, v0
	v_cmp_gt_u32_e64 s[10:11], v2, v209
	v_or_b32_e32 v2, 5, v0
	v_cmp_gt_u32_e64 s[12:13], v2, v209
	v_or_b32_e32 v2, 6, v0
	v_cmp_gt_u32_e64 s[14:15], v2, v209
	v_or_b32_e32 v2, 7, v0
	v_cmp_gt_u32_e64 s[16:17], v2, v209
	v_or_b32_e32 v2, 16, v0
	v_cmp_gt_u32_e64 s[18:19], v2, v209
	v_or_b32_e32 v2, 17, v0
	v_cmp_gt_u32_e64 s[20:21], v2, v209
	v_or_b32_e32 v2, 18, v0
	s_add_i32 s2, 0, 0x18000
	v_cmp_gt_u32_e64 s[22:23], v2, v209
	v_or_b32_e32 v2, 19, v0
	v_bitop3_b32 v15, v12, v15, 1 bitop3:0x36
	v_cmp_gt_u32_e64 s[24:25], v2, v209
	v_or_b32_e32 v2, 20, v0
	s_add_u32 s48, s60, 0xe000000
	v_lshlrev_b32_e32 v16, 4, v16
	v_lshlrev_b32_e32 v15, 4, v15
	v_cmp_gt_u32_e64 s[26:27], v2, v209
	v_or_b32_e32 v2, 21, v0
	s_addc_u32 s49, s61, 0
	v_lshl_add_u32 v211, v206, 4, s2
	v_lshrrev_b32_e32 v212, 4, v206
	v_add3_u32 v223, v10, v16, v14
	v_add3_u32 v225, v10, v15, v14
	v_cmp_gt_u32_e64 s[2:3], v0, v209
	v_cmp_lt_u32_e64 s[4:5], v0, v209
	v_cmp_gt_u32_e64 s[28:29], v2, v209
	v_or_b32_e32 v2, 22, v0
	v_or_b32_e32 v0, 23, v0
	s_add_u32 s54, s60, 0x12000000
	v_and_b32_e32 v213, 15, v207
	v_lshlrev_b32_e32 v214, 2, v212
	v_add_u32_e32 v216, 0xc000, v215
	v_add_u32_e32 v218, 0xc400, v217
	v_add_u32_e32 v220, 0xc000, v219
	v_add_u32_e32 v222, 0xc400, v221
	v_add_u32_e32 v224, 0xc000, v223
	v_add_u32_e32 v226, 0xc400, v225
	v_add_u32_e32 v228, 0xc000, v227
	v_add_u32_e32 v230, 0xc400, v229
	v_cmp_gt_u32_e64 s[30:31], v2, v209
	v_cmp_gt_u32_e64 s[34:35], v0, v209
	s_addc_u32 s55, s61, 0
	v_sub_u32_e32 v231, 0, v209
	s_movk_i32 s70, 0xf0
	s_add_i32 s71, 0, 0x10000
	s_add_i32 s72, 0, 0x14000
	v_mov_b32_e32 v232, 0x358637bd
	v_mov_b32_e32 v233, 0x42800000
	v_add_u32_e32 v234, 0, v8
	v_add_u32_e32 v235, 0, v7
	v_add_u32_e32 v236, 0, v4
	v_add_u32_e32 v237, 0, v3
	v_add_u32_e32 v238, 0, v1
	v_add_u32_e32 v239, 0, v9
	v_add_u32_e32 v240, 0, v6
	v_add_u32_e32 v241, 0, v5
	v_mov_b32_e32 v242, 0xff800000
	v_mov_b32_e32 v181, 0x41000000
	s_and_b32 s73, s33, 7
	s_lshl_b32 s73, s73, 4
	s_lshr_b32 s99, s33, 3
	s_and_b32 s100, s99, 15
	s_add_i32 s73, s73, s100
	s_lshr_b32 s100, s99, 4
	s_lshl_b32 s100, s100, 7
	s_add_i32 s73, s73, s100
	s_branch .LBB0_736

.LBB0_763:
	ds_read_b128 v[160:163], v237 offset:8192
	ds_read_b128 v[164:167], v189
	ds_read_b128 v[202:205], v235 offset:8192
	ds_read_b128 v[244:247], v189 offset:4096
	ds_read_b128 v[248:251], v236 offset:8192
	ds_read_b128 v[252:255], v189 offset:1024
	s_cmp_lg_u32 s79, s40
	s_waitcnt lgkmcnt(4)
	v_mfma_f32_32x32x16_bf16 v[144:159], v[160:163], v[164:167], v[128:143]
	s_waitcnt lgkmcnt(2)
	v_mfma_f32_32x32x16_bf16 v[160:175], v[202:205], v[244:247], v[128:143]
	ds_read_b128 v[202:205], v234 offset:8192
	ds_read_b128 v[244:247], v189 offset:5120
	v_add_u32_e32 v215, s40, v185
	v_add_u32_e32 v215, 0xe0, v215
	v_cvt_f32_i32_e32 v215, v215
	v_add_f32_e32 v227, 0x41000000, v199
	v_mul_f32_e32 v200, v184, v215
	v_add_f32_e32 v215, 0x41000000, v201
	s_waitcnt lgkmcnt(2)
	v_mfma_f32_32x32x16_bf16 v[144:159], v[248:251], v[252:255], v[144:159]
	ds_read_b128 v[248:251], v241 offset:8192
	ds_read_b128 v[252:255], v189 offset:2048
	s_waitcnt lgkmcnt(2)
	v_mfma_f32_32x32x16_bf16 v[160:175], v[202:205], v[244:247], v[160:175]
	ds_read_b128 v[202:205], v239 offset:8192
	ds_read_b128 v[244:247], v189 offset:6144
	s_waitcnt lgkmcnt(2)
	v_mfma_f32_32x32x16_bf16 v[144:159], v[248:251], v[252:255], v[144:159]
	ds_read_b128 v[248:251], v240 offset:8192
	ds_read_b128 v[252:255], v189 offset:3072
	s_waitcnt lgkmcnt(2)
	v_mfma_f32_32x32x16_bf16 v[160:175], v[202:205], v[244:247], v[160:175]
	ds_read_b128 v[202:205], v238 offset:8192
	ds_read_b128 v[244:247], v189 offset:7168
	s_waitcnt lgkmcnt(2)
	v_mfma_f32_32x32x16_bf16 v[144:159], v[248:251], v[252:255], v[144:159]
	s_waitcnt lgkmcnt(0)
	v_mfma_f32_32x32x16_bf16 v[160:175], v[202:205], v[244:247], v[160:175]
	ds_read_b64_tr_b16 v[202:203], v216 offset:8192
	ds_read_b64_tr_b16 v[204:205], v218 offset:8192
	ds_read_b64_tr_b16 v[244:245], v220 offset:8192
	ds_read_b64_tr_b16 v[246:247], v222 offset:8192
	ds_read_b64_tr_b16 v[248:249], v224 offset:8192
	ds_read_b64_tr_b16 v[250:251], v226 offset:8192
	ds_read_b64_tr_b16 v[252:253], v228 offset:8192
	ds_read_b64_tr_b16 v[254:255], v230 offset:8192
	s_cbranch_scc0 .Lat1_diag
.Lat1_go:
	v_sub_f32_e32 v180, v200, v199
	v_sub_f32_e32 v198, v200, v201
	s_nop 0
	v_max3_f32 v217, v144, v145, v146
	v_max3_f32 v219, v160, v161, v162
	v_max3_f32 v221, v147, v148, v149
	v_max3_f32 v225, v163, v164, v165
	v_max3_f32 v223, v150, v151, v152
	v_max3_f32 v229, v166, v167, v168
	v_add_f32_e32 v144, v144, v180
	v_add_f32_e32 v160, v160, v198
	v_max3_f32 v217, v217, v221, v223
	v_exp_f32_e32 v144, v144
	v_exp_f32_e32 v160, v160
	v_max3_f32 v219, v219, v225, v229
	v_add_f32_e32 v145, v145, v180
	v_add_f32_e32 v161, v161, v198
	v_max3_f32 v221, v153, v154, v155
	v_exp_f32_e32 v145, v145
	v_exp_f32_e32 v161, v161
	v_max3_f32 v225, v169, v170, v171
	v_add_f32_e32 v146, v146, v180
	v_add_f32_e32 v162, v162, v198
	v_max3_f32 v223, v156, v157, v158
	v_exp_f32_e32 v146, v146
	v_exp_f32_e32 v162, v162
	v_max3_f32 v229, v172, v173, v174
	v_add_f32_e32 v147, v147, v180
	v_add_f32_e32 v163, v163, v198
	v_max3_f32 v221, v221, v223, v159
	v_exp_f32_e32 v147, v147
	v_exp_f32_e32 v163, v163
	v_max3_f32 v225, v225, v229, v175
	v_add_f32_e32 v148, v148, v180
	v_add_f32_e32 v164, v164, v198
	v_max_f32_e32 v217, v217, v221
	v_exp_f32_e32 v148, v148
	v_exp_f32_e32 v164, v164
	v_max_f32_e32 v219, v219, v225
	v_add_f32_e32 v149, v149, v180
	v_add_f32_e32 v165, v165, v198
	v_add_f32_e32 v221, v200, v217
	v_exp_f32_e32 v149, v149
	v_exp_f32_e32 v165, v165
	v_add_f32_e32 v225, v200, v219
	v_add_f32_e32 v150, v150, v180
	v_add_f32_e32 v166, v166, v198
	v_cmp_gt_f32_e32 vcc, v221, v227
	v_exp_f32_e32 v150, v150
	v_exp_f32_e32 v166, v166
	v_cmp_gt_f32_e64 s[0:1], v225, v215
	v_add_f32_e32 v151, v151, v180
	v_add_f32_e32 v167, v167, v198
	v_exp_f32_e32 v151, v151
	v_exp_f32_e32 v167, v167
	v_add_f32_e32 v215, v144, v145
	v_add_f32_e32 v217, v160, v161
	v_add_f32_e32 v215, v215, v146
	v_add_f32_e32 v217, v217, v162
	v_add_f32_e32 v215, v215, v147
	v_add_f32_e32 v217, v217, v163
	v_add_f32_e32 v215, v215, v148
	v_add_f32_e32 v217, v217, v164
	v_add_f32_e32 v215, v215, v149
	v_add_f32_e32 v217, v217, v165
	v_add_f32_e32 v215, v215, v150
	v_add_f32_e32 v217, v217, v166
	v_add_f32_e32 v215, v215, v151
	v_add_f32_e32 v217, v217, v167
	v_cvt_pk_bf16_f32 v144, v144, v145
	v_cvt_pk_bf16_f32 v160, v160, v161
	v_cvt_pk_bf16_f32 v145, v146, v147
	v_cvt_pk_bf16_f32 v161, v162, v163
	v_cvt_pk_bf16_f32 v146, v148, v149
	v_cvt_pk_bf16_f32 v162, v164, v165
	v_cvt_pk_bf16_f32 v147, v150, v151
	v_cvt_pk_bf16_f32 v163, v166, v167
	ds_read_b64_tr_b16 v[148:149], v216 offset:12288
	ds_read_b64_tr_b16 v[150:151], v218 offset:12288
	ds_read_b64_tr_b16 v[164:165], v220 offset:12288
	ds_read_b64_tr_b16 v[166:167], v222 offset:12288
	s_or_b64 vcc, vcc, s[0:1]
	s_cbranch_vccnz .Lat1_redo
	s_waitcnt lgkmcnt(4)
	v_mfma_f32_32x32x16_bf16 v[112:127], v[202:205], v[144:147], v[112:127]
	v_add_f32_e32 v152, v152, v180
	v_add_f32_e32 v168, v168, v198
	v_exp_f32_e32 v152, v152
	v_exp_f32_e32 v168, v168
	v_mfma_f32_32x32x16_bf16 v[96:111], v[202:205], v[160:163], v[96:111]
	v_add_f32_e32 v153, v153, v180
	v_add_f32_e32 v169, v169, v198
	v_exp_f32_e32 v153, v153
	v_exp_f32_e32 v169, v169
	ds_read_b64_tr_b16 v[202:203], v224 offset:12288
	ds_read_b64_tr_b16 v[204:205], v226 offset:12288
	v_mfma_f32_32x32x16_bf16 v[64:79], v[244:247], v[144:147], v[64:79]
	v_add_f32_e32 v154, v154, v180
	v_add_f32_e32 v170, v170, v198
	v_exp_f32_e32 v154, v154
	v_exp_f32_e32 v170, v170
	v_mfma_f32_32x32x16_bf16 v[80:95], v[244:247], v[160:163], v[80:95]
	v_add_f32_e32 v155, v155, v180
	v_add_f32_e32 v171, v171, v198
	v_exp_f32_e32 v155, v155
	v_exp_f32_e32 v171, v171
	ds_read_b64_tr_b16 v[244:245], v228 offset:12288
	ds_read_b64_tr_b16 v[246:247], v230 offset:12288
	v_mfma_f32_32x32x16_bf16 v[32:47], v[248:251], v[144:147], v[32:47]
	v_add_f32_e32 v156, v156, v180
	v_add_f32_e32 v172, v172, v198
	v_exp_f32_e32 v156, v156
	v_exp_f32_e32 v172, v172
	v_mfma_f32_32x32x16_bf16 v[48:63], v[248:251], v[160:163], v[48:63]
	v_add_f32_e32 v157, v157, v180
	v_add_f32_e32 v173, v173, v198
	v_exp_f32_e32 v157, v157
	v_exp_f32_e32 v173, v173
	v_mfma_f32_32x32x16_bf16 v[0:15], v[252:255], v[144:147], v[0:15]
	v_add_f32_e32 v158, v158, v180
	v_add_f32_e32 v174, v174, v198
	v_exp_f32_e32 v158, v158
	v_exp_f32_e32 v174, v174
	v_mfma_f32_32x32x16_bf16 v[16:31], v[252:255], v[160:163], v[16:31]
	v_add_f32_e32 v159, v159, v180
	v_add_f32_e32 v175, v175, v198
	v_exp_f32_e32 v159, v159
	v_exp_f32_e32 v175, v175
	v_cvt_pk_bf16_f32 v248, v152, v153
	v_cvt_pk_bf16_f32 v252, v168, v169
	v_cvt_pk_bf16_f32 v249, v154, v155
	v_cvt_pk_bf16_f32 v253, v170, v171
	v_cvt_pk_bf16_f32 v250, v156, v157
	v_cvt_pk_bf16_f32 v254, v172, v173
	v_cvt_pk_bf16_f32 v251, v158, v159
	v_cvt_pk_bf16_f32 v255, v174, v175
	s_nop 0
	s_waitcnt lgkmcnt(6)
	v_mfma_f32_32x32x16_bf16 v[112:127], v[148:151], v[248:251], v[112:127]
	v_add_f32_e32 v215, v215, v152
	v_add_f32_e32 v217, v217, v168
	v_mfma_f32_32x32x16_bf16 v[96:111], v[148:151], v[252:255], v[96:111]
	v_add_f32_e32 v215, v215, v153
	v_add_f32_e32 v217, v217, v169
	v_add_f32_e32 v215, v215, v154
	s_waitcnt lgkmcnt(4)
	v_mfma_f32_32x32x16_bf16 v[64:79], v[164:167], v[248:251], v[64:79]
	v_add_f32_e32 v217, v217, v170
	v_add_f32_e32 v215, v215, v155
	v_mfma_f32_32x32x16_bf16 v[80:95], v[164:167], v[252:255], v[80:95]
	v_add_f32_e32 v217, v217, v171
	v_add_f32_e32 v215, v215, v156
	v_add_f32_e32 v217, v217, v172
	s_waitcnt lgkmcnt(2)
	v_mfma_f32_32x32x16_bf16 v[32:47], v[202:205], v[248:251], v[32:47]
	v_add_f32_e32 v215, v215, v157
	v_add_f32_e32 v217, v217, v173
	v_mfma_f32_32x32x16_bf16 v[48:63], v[202:205], v[252:255], v[48:63]
	v_add_f32_e32 v215, v215, v158
	v_add_f32_e32 v217, v217, v174
	v_add_f32_e32 v215, v215, v159
	s_waitcnt lgkmcnt(0)
	v_mfma_f32_32x32x16_bf16 v[0:15], v[244:247], v[248:251], v[0:15]
	v_add_f32_e32 v217, v217, v175
	v_add_f32_e32 v197, v197, v215
	v_mfma_f32_32x32x16_bf16 v[16:31], v[244:247], v[252:255], v[16:31]
	v_add_f32_e32 v196, v196, v217
	s_cmp_gt_i32 s38, s84
	s_cbranch_scc1 .LBB0_759
.LBB0_768:
	ds_read_b128 v[160:163], v237
	ds_read_b128 v[164:167], v189
	ds_read_b128 v[202:205], v235
	ds_read_b128 v[244:247], v189 offset:4096
	ds_read_b128 v[248:251], v236
	ds_read_b128 v[252:255], v189 offset:1024
	s_cmp_lg_u32 s67, s40
	s_waitcnt lgkmcnt(4)
	v_mfma_f32_32x32x16_bf16 v[144:159], v[160:163], v[164:167], v[128:143]
	s_waitcnt lgkmcnt(2)
	v_mfma_f32_32x32x16_bf16 v[160:175], v[202:205], v[244:247], v[128:143]
	ds_read_b128 v[202:205], v234
	ds_read_b128 v[244:247], v189 offset:5120
	v_add_u32_e32 v215, s40, v185
	v_add_u32_e32 v215, 0xc0, v215
	v_cvt_f32_i32_e32 v215, v215
	v_add_f32_e32 v227, 0x41000000, v199
	v_mul_f32_e32 v200, v184, v215
	v_add_f32_e32 v215, 0x41000000, v201
	s_waitcnt lgkmcnt(2)
	v_mfma_f32_32x32x16_bf16 v[144:159], v[248:251], v[252:255], v[144:159]
	ds_read_b128 v[248:251], v241
	ds_read_b128 v[252:255], v189 offset:2048
	s_waitcnt lgkmcnt(2)
	v_mfma_f32_32x32x16_bf16 v[160:175], v[202:205], v[244:247], v[160:175]
	ds_read_b128 v[202:205], v239
	ds_read_b128 v[244:247], v189 offset:6144
	s_waitcnt lgkmcnt(2)
	v_mfma_f32_32x32x16_bf16 v[144:159], v[248:251], v[252:255], v[144:159]
	ds_read_b128 v[248:251], v240
	ds_read_b128 v[252:255], v189 offset:3072
	s_waitcnt lgkmcnt(2)
	v_mfma_f32_32x32x16_bf16 v[160:175], v[202:205], v[244:247], v[160:175]
	ds_read_b128 v[202:205], v238
	ds_read_b128 v[244:247], v189 offset:7168
	s_waitcnt lgkmcnt(2)
	v_mfma_f32_32x32x16_bf16 v[144:159], v[248:251], v[252:255], v[144:159]
	s_waitcnt lgkmcnt(0)
	v_mfma_f32_32x32x16_bf16 v[160:175], v[202:205], v[244:247], v[160:175]
	ds_read_b64_tr_b16 v[202:203], v216
	ds_read_b64_tr_b16 v[204:205], v218
	ds_read_b64_tr_b16 v[244:245], v220
	ds_read_b64_tr_b16 v[246:247], v222
	ds_read_b64_tr_b16 v[248:249], v224
	ds_read_b64_tr_b16 v[250:251], v226
	ds_read_b64_tr_b16 v[252:253], v228
	ds_read_b64_tr_b16 v[254:255], v230
	s_cbranch_scc0 .Lat2_diag
.Lat2_go:
	v_sub_f32_e32 v180, v200, v199
	v_sub_f32_e32 v198, v200, v201
	s_nop 0
	v_max3_f32 v217, v144, v145, v146
	v_max3_f32 v219, v160, v161, v162
	v_max3_f32 v221, v147, v148, v149
	v_max3_f32 v225, v163, v164, v165
	v_max3_f32 v223, v150, v151, v152
	v_max3_f32 v229, v166, v167, v168
	v_add_f32_e32 v144, v144, v180
	v_add_f32_e32 v160, v160, v198
	v_max3_f32 v217, v217, v221, v223
	v_exp_f32_e32 v144, v144
	v_exp_f32_e32 v160, v160
	v_max3_f32 v219, v219, v225, v229
	v_add_f32_e32 v145, v145, v180
	v_add_f32_e32 v161, v161, v198
	v_max3_f32 v221, v153, v154, v155
	v_exp_f32_e32 v145, v145
	v_exp_f32_e32 v161, v161
	v_max3_f32 v225, v169, v170, v171
	v_add_f32_e32 v146, v146, v180
	v_add_f32_e32 v162, v162, v198
	v_max3_f32 v223, v156, v157, v158
	v_exp_f32_e32 v146, v146
	v_exp_f32_e32 v162, v162
	v_max3_f32 v229, v172, v173, v174
	v_add_f32_e32 v147, v147, v180
	v_add_f32_e32 v163, v163, v198
	v_max3_f32 v221, v221, v223, v159
	v_exp_f32_e32 v147, v147
	v_exp_f32_e32 v163, v163
	v_max3_f32 v225, v225, v229, v175
	v_add_f32_e32 v148, v148, v180
	v_add_f32_e32 v164, v164, v198
	v_max_f32_e32 v217, v217, v221
	v_exp_f32_e32 v148, v148
	v_exp_f32_e32 v164, v164
	v_max_f32_e32 v219, v219, v225
	v_add_f32_e32 v149, v149, v180
	v_add_f32_e32 v165, v165, v198
	v_add_f32_e32 v221, v200, v217
	v_exp_f32_e32 v149, v149
	v_exp_f32_e32 v165, v165
	v_add_f32_e32 v225, v200, v219
	v_add_f32_e32 v150, v150, v180
	v_add_f32_e32 v166, v166, v198
	v_cmp_gt_f32_e32 vcc, v221, v227
	v_exp_f32_e32 v150, v150
	v_exp_f32_e32 v166, v166
	v_cmp_gt_f32_e64 s[0:1], v225, v215
	v_add_f32_e32 v151, v151, v180
	v_add_f32_e32 v167, v167, v198
	v_exp_f32_e32 v151, v151
	v_exp_f32_e32 v167, v167
	v_add_f32_e32 v215, v144, v145
	v_add_f32_e32 v217, v160, v161
	v_add_f32_e32 v215, v215, v146
	v_add_f32_e32 v217, v217, v162
	v_add_f32_e32 v215, v215, v147
	v_add_f32_e32 v217, v217, v163
	v_add_f32_e32 v215, v215, v148
	v_add_f32_e32 v217, v217, v164
	v_add_f32_e32 v215, v215, v149
	v_add_f32_e32 v217, v217, v165
	v_add_f32_e32 v215, v215, v150
	v_add_f32_e32 v217, v217, v166
	v_add_f32_e32 v215, v215, v151
	v_add_f32_e32 v217, v217, v167
	v_cvt_pk_bf16_f32 v144, v144, v145
	v_cvt_pk_bf16_f32 v160, v160, v161
	v_cvt_pk_bf16_f32 v145, v146, v147
	v_cvt_pk_bf16_f32 v161, v162, v163
	v_cvt_pk_bf16_f32 v146, v148, v149
	v_cvt_pk_bf16_f32 v162, v164, v165
	v_cvt_pk_bf16_f32 v147, v150, v151
	v_cvt_pk_bf16_f32 v163, v166, v167
	ds_read_b64_tr_b16 v[148:149], v216 offset:4096
	ds_read_b64_tr_b16 v[150:151], v218 offset:4096
	ds_read_b64_tr_b16 v[164:165], v220 offset:4096
	ds_read_b64_tr_b16 v[166:167], v222 offset:4096
	s_or_b64 vcc, vcc, s[0:1]
	s_cbranch_vccnz .Lat2_redo
	s_waitcnt lgkmcnt(4)
	v_mfma_f32_32x32x16_bf16 v[112:127], v[202:205], v[144:147], v[112:127]
	v_add_f32_e32 v152, v152, v180
	v_add_f32_e32 v168, v168, v198
	v_exp_f32_e32 v152, v152
	v_exp_f32_e32 v168, v168
	v_mfma_f32_32x32x16_bf16 v[96:111], v[202:205], v[160:163], v[96:111]
	v_add_f32_e32 v153, v153, v180
	v_add_f32_e32 v169, v169, v198
	v_exp_f32_e32 v153, v153
	v_exp_f32_e32 v169, v169
	ds_read_b64_tr_b16 v[202:203], v224 offset:4096
	ds_read_b64_tr_b16 v[204:205], v226 offset:4096
	v_mfma_f32_32x32x16_bf16 v[64:79], v[244:247], v[144:147], v[64:79]
	v_add_f32_e32 v154, v154, v180
	v_add_f32_e32 v170, v170, v198
	v_exp_f32_e32 v154, v154
	v_exp_f32_e32 v170, v170
	v_mfma_f32_32x32x16_bf16 v[80:95], v[244:247], v[160:163], v[80:95]
	v_add_f32_e32 v155, v155, v180
	v_add_f32_e32 v171, v171, v198
	v_exp_f32_e32 v155, v155
	v_exp_f32_e32 v171, v171
	ds_read_b64_tr_b16 v[244:245], v228 offset:4096
	ds_read_b64_tr_b16 v[246:247], v230 offset:4096
	v_mfma_f32_32x32x16_bf16 v[32:47], v[248:251], v[144:147], v[32:47]
	v_add_f32_e32 v156, v156, v180
	v_add_f32_e32 v172, v172, v198
	v_exp_f32_e32 v156, v156
	v_exp_f32_e32 v172, v172
	v_mfma_f32_32x32x16_bf16 v[48:63], v[248:251], v[160:163], v[48:63]
	v_add_f32_e32 v157, v157, v180
	v_add_f32_e32 v173, v173, v198
	v_exp_f32_e32 v157, v157
	v_exp_f32_e32 v173, v173
	v_mfma_f32_32x32x16_bf16 v[0:15], v[252:255], v[144:147], v[0:15]
	v_add_f32_e32 v158, v158, v180
	v_add_f32_e32 v174, v174, v198
	v_exp_f32_e32 v158, v158
	v_exp_f32_e32 v174, v174
	v_mfma_f32_32x32x16_bf16 v[16:31], v[252:255], v[160:163], v[16:31]
	v_add_f32_e32 v159, v159, v180
	v_add_f32_e32 v175, v175, v198
	v_exp_f32_e32 v159, v159
	v_exp_f32_e32 v175, v175
	v_cvt_pk_bf16_f32 v248, v152, v153
	v_cvt_pk_bf16_f32 v252, v168, v169
	v_cvt_pk_bf16_f32 v249, v154, v155
	v_cvt_pk_bf16_f32 v253, v170, v171
	v_cvt_pk_bf16_f32 v250, v156, v157
	v_cvt_pk_bf16_f32 v254, v172, v173
	v_cvt_pk_bf16_f32 v251, v158, v159
	v_cvt_pk_bf16_f32 v255, v174, v175
	s_nop 0
	s_waitcnt lgkmcnt(6)
	v_mfma_f32_32x32x16_bf16 v[112:127], v[148:151], v[248:251], v[112:127]
	v_add_f32_e32 v215, v215, v152
	v_add_f32_e32 v217, v217, v168
	v_mfma_f32_32x32x16_bf16 v[96:111], v[148:151], v[252:255], v[96:111]
	v_add_f32_e32 v215, v215, v153
	v_add_f32_e32 v217, v217, v169
	v_add_f32_e32 v215, v215, v154
	s_waitcnt lgkmcnt(4)
	v_mfma_f32_32x32x16_bf16 v[64:79], v[164:167], v[248:251], v[64:79]
	v_add_f32_e32 v217, v217, v170
	v_add_f32_e32 v215, v215, v155
	v_mfma_f32_32x32x16_bf16 v[80:95], v[164:167], v[252:255], v[80:95]
	v_add_f32_e32 v217, v217, v171
	v_add_f32_e32 v215, v215, v156
	v_add_f32_e32 v217, v217, v172
	s_waitcnt lgkmcnt(2)
	v_mfma_f32_32x32x16_bf16 v[32:47], v[202:205], v[248:251], v[32:47]
	v_add_f32_e32 v215, v215, v157
	v_add_f32_e32 v217, v217, v173
	v_mfma_f32_32x32x16_bf16 v[48:63], v[202:205], v[252:255], v[48:63]
	v_add_f32_e32 v215, v215, v158
	v_add_f32_e32 v217, v217, v174
	v_add_f32_e32 v215, v215, v159
	s_waitcnt lgkmcnt(0)
	v_mfma_f32_32x32x16_bf16 v[0:15], v[244:247], v[248:251], v[0:15]
	v_add_f32_e32 v217, v217, v175
	v_add_f32_e32 v197, v197, v215
	v_mfma_f32_32x32x16_bf16 v[16:31], v[244:247], v[252:255], v[16:31]
	v_add_f32_e32 v196, v196, v217
	s_add_i32 s78, s41, 1
	s_cmp_ge_u32 s78, s85
	s_cbranch_scc1 .LBB0_778

.LBB0_787:
	ds_read_b128 v[160:163], v237 offset:24576
	ds_read_b128 v[164:167], v189
	ds_read_b128 v[202:205], v235 offset:24576
	ds_read_b128 v[244:247], v189 offset:4096
	ds_read_b128 v[248:251], v236 offset:24576
	ds_read_b128 v[252:255], v189 offset:1024
	s_cmp_lg_u32 s66, s40
	s_waitcnt lgkmcnt(4)
	v_mfma_f32_32x32x16_bf16 v[144:159], v[160:163], v[164:167], v[128:143]
	s_waitcnt lgkmcnt(2)
	v_mfma_f32_32x32x16_bf16 v[160:175], v[202:205], v[244:247], v[128:143]
	ds_read_b128 v[202:205], v234 offset:24576
	ds_read_b128 v[244:247], v189 offset:5120
	v_add_u32_e32 v215, s40, v185
	v_add_u32_e32 v215, 0xa0, v215
	v_cvt_f32_i32_e32 v215, v215
	v_add_f32_e32 v227, 0x41000000, v199
	v_mul_f32_e32 v200, v184, v215
	v_add_f32_e32 v215, 0x41000000, v201
	s_waitcnt lgkmcnt(2)
	v_mfma_f32_32x32x16_bf16 v[144:159], v[248:251], v[252:255], v[144:159]
	ds_read_b128 v[248:251], v241 offset:24576
	ds_read_b128 v[252:255], v189 offset:2048
	s_waitcnt lgkmcnt(2)
	v_mfma_f32_32x32x16_bf16 v[160:175], v[202:205], v[244:247], v[160:175]
	ds_read_b128 v[202:205], v239 offset:24576
	ds_read_b128 v[244:247], v189 offset:6144
	s_waitcnt lgkmcnt(2)
	v_mfma_f32_32x32x16_bf16 v[144:159], v[248:251], v[252:255], v[144:159]
	ds_read_b128 v[248:251], v240 offset:24576
	ds_read_b128 v[252:255], v189 offset:3072
	s_waitcnt lgkmcnt(2)
	v_mfma_f32_32x32x16_bf16 v[160:175], v[202:205], v[244:247], v[160:175]
	ds_read_b128 v[202:205], v238 offset:24576
	ds_read_b128 v[244:247], v189 offset:7168
	s_waitcnt lgkmcnt(2)
	v_mfma_f32_32x32x16_bf16 v[144:159], v[248:251], v[252:255], v[144:159]
	s_waitcnt lgkmcnt(0)
	v_mfma_f32_32x32x16_bf16 v[160:175], v[202:205], v[244:247], v[160:175]
	ds_read_b64_tr_b16 v[202:203], v216 offset:24576
	ds_read_b64_tr_b16 v[204:205], v218 offset:24576
	ds_read_b64_tr_b16 v[244:245], v220 offset:24576
	ds_read_b64_tr_b16 v[246:247], v222 offset:24576
	ds_read_b64_tr_b16 v[248:249], v224 offset:24576
	ds_read_b64_tr_b16 v[250:251], v226 offset:24576
	ds_read_b64_tr_b16 v[252:253], v228 offset:24576
	ds_read_b64_tr_b16 v[254:255], v230 offset:24576
	s_cbranch_scc0 .Lat3_diag
.Lat3_go:
	v_sub_f32_e32 v180, v200, v199
	v_sub_f32_e32 v198, v200, v201
	s_nop 0
	v_max3_f32 v217, v144, v145, v146
	v_max3_f32 v219, v160, v161, v162
	v_max3_f32 v221, v147, v148, v149
	v_max3_f32 v225, v163, v164, v165
	v_max3_f32 v223, v150, v151, v152
	v_max3_f32 v229, v166, v167, v168
	v_add_f32_e32 v144, v144, v180
	v_add_f32_e32 v160, v160, v198
	v_max3_f32 v217, v217, v221, v223
	v_exp_f32_e32 v144, v144
	v_exp_f32_e32 v160, v160
	v_max3_f32 v219, v219, v225, v229
	v_add_f32_e32 v145, v145, v180
	v_add_f32_e32 v161, v161, v198
	v_max3_f32 v221, v153, v154, v155
	v_exp_f32_e32 v145, v145
	v_exp_f32_e32 v161, v161
	v_max3_f32 v225, v169, v170, v171
	v_add_f32_e32 v146, v146, v180
	v_add_f32_e32 v162, v162, v198
	v_max3_f32 v223, v156, v157, v158
	v_exp_f32_e32 v146, v146
	v_exp_f32_e32 v162, v162
	v_max3_f32 v229, v172, v173, v174
	v_add_f32_e32 v147, v147, v180
	v_add_f32_e32 v163, v163, v198
	v_max3_f32 v221, v221, v223, v159
	v_exp_f32_e32 v147, v147
	v_exp_f32_e32 v163, v163
	v_max3_f32 v225, v225, v229, v175
	v_add_f32_e32 v148, v148, v180
	v_add_f32_e32 v164, v164, v198
	v_max_f32_e32 v217, v217, v221
	v_exp_f32_e32 v148, v148
	v_exp_f32_e32 v164, v164
	v_max_f32_e32 v219, v219, v225
	v_add_f32_e32 v149, v149, v180
	v_add_f32_e32 v165, v165, v198
	v_add_f32_e32 v221, v200, v217
	v_exp_f32_e32 v149, v149
	v_exp_f32_e32 v165, v165
	v_add_f32_e32 v225, v200, v219
	v_add_f32_e32 v150, v150, v180
	v_add_f32_e32 v166, v166, v198
	v_cmp_gt_f32_e32 vcc, v221, v227
	v_exp_f32_e32 v150, v150
	v_exp_f32_e32 v166, v166
	v_cmp_gt_f32_e64 s[0:1], v225, v215
	v_add_f32_e32 v151, v151, v180
	v_add_f32_e32 v167, v167, v198
	v_exp_f32_e32 v151, v151
	v_exp_f32_e32 v167, v167
	v_add_f32_e32 v215, v144, v145
	v_add_f32_e32 v217, v160, v161
	v_add_f32_e32 v215, v215, v146
	v_add_f32_e32 v217, v217, v162
	v_add_f32_e32 v215, v215, v147
	v_add_f32_e32 v217, v217, v163
	v_add_f32_e32 v215, v215, v148
	v_add_f32_e32 v217, v217, v164
	v_add_f32_e32 v215, v215, v149
	v_add_f32_e32 v217, v217, v165
	v_add_f32_e32 v215, v215, v150
	v_add_f32_e32 v217, v217, v166
	v_add_f32_e32 v215, v215, v151
	v_add_f32_e32 v217, v217, v167
	v_cvt_pk_bf16_f32 v144, v144, v145
	v_cvt_pk_bf16_f32 v160, v160, v161
	v_cvt_pk_bf16_f32 v145, v146, v147
	v_cvt_pk_bf16_f32 v161, v162, v163
	v_cvt_pk_bf16_f32 v146, v148, v149
	v_cvt_pk_bf16_f32 v162, v164, v165
	v_cvt_pk_bf16_f32 v147, v150, v151
	v_cvt_pk_bf16_f32 v163, v166, v167
	ds_read_b64_tr_b16 v[148:149], v216 offset:28672
	ds_read_b64_tr_b16 v[150:151], v218 offset:28672
	ds_read_b64_tr_b16 v[164:165], v220 offset:28672
	ds_read_b64_tr_b16 v[166:167], v222 offset:28672
	s_or_b64 vcc, vcc, s[0:1]
	s_cbranch_vccnz .Lat3_redo
	s_waitcnt lgkmcnt(4)
	v_mfma_f32_32x32x16_bf16 v[112:127], v[202:205], v[144:147], v[112:127]
	v_add_f32_e32 v152, v152, v180
	v_add_f32_e32 v168, v168, v198
	v_exp_f32_e32 v152, v152
	v_exp_f32_e32 v168, v168
	v_mfma_f32_32x32x16_bf16 v[96:111], v[202:205], v[160:163], v[96:111]
	v_add_f32_e32 v153, v153, v180
	v_add_f32_e32 v169, v169, v198
	v_exp_f32_e32 v153, v153
	v_exp_f32_e32 v169, v169
	ds_read_b64_tr_b16 v[202:203], v224 offset:28672
	ds_read_b64_tr_b16 v[204:205], v226 offset:28672
	v_mfma_f32_32x32x16_bf16 v[64:79], v[244:247], v[144:147], v[64:79]
	v_add_f32_e32 v154, v154, v180
	v_add_f32_e32 v170, v170, v198
	v_exp_f32_e32 v154, v154
	v_exp_f32_e32 v170, v170
	v_mfma_f32_32x32x16_bf16 v[80:95], v[244:247], v[160:163], v[80:95]
	v_add_f32_e32 v155, v155, v180
	v_add_f32_e32 v171, v171, v198
	v_exp_f32_e32 v155, v155
	v_exp_f32_e32 v171, v171
	ds_read_b64_tr_b16 v[244:245], v228 offset:28672
	ds_read_b64_tr_b16 v[246:247], v230 offset:28672
	v_mfma_f32_32x32x16_bf16 v[32:47], v[248:251], v[144:147], v[32:47]
	v_add_f32_e32 v156, v156, v180
	v_add_f32_e32 v172, v172, v198
	v_exp_f32_e32 v156, v156
	v_exp_f32_e32 v172, v172
	v_mfma_f32_32x32x16_bf16 v[48:63], v[248:251], v[160:163], v[48:63]
	v_add_f32_e32 v157, v157, v180
	v_add_f32_e32 v173, v173, v198
	v_exp_f32_e32 v157, v157
	v_exp_f32_e32 v173, v173
	v_mfma_f32_32x32x16_bf16 v[0:15], v[252:255], v[144:147], v[0:15]
	v_add_f32_e32 v158, v158, v180
	v_add_f32_e32 v174, v174, v198
	v_exp_f32_e32 v158, v158
	v_exp_f32_e32 v174, v174
	v_mfma_f32_32x32x16_bf16 v[16:31], v[252:255], v[160:163], v[16:31]
	v_add_f32_e32 v159, v159, v180
	v_add_f32_e32 v175, v175, v198
	v_exp_f32_e32 v159, v159
	v_exp_f32_e32 v175, v175
	v_cvt_pk_bf16_f32 v248, v152, v153
	v_cvt_pk_bf16_f32 v252, v168, v169
	v_cvt_pk_bf16_f32 v249, v154, v155
	v_cvt_pk_bf16_f32 v253, v170, v171
	v_cvt_pk_bf16_f32 v250, v156, v157
	v_cvt_pk_bf16_f32 v254, v172, v173
	v_cvt_pk_bf16_f32 v251, v158, v159
	v_cvt_pk_bf16_f32 v255, v174, v175
	s_nop 0
	s_waitcnt lgkmcnt(6)
	v_mfma_f32_32x32x16_bf16 v[112:127], v[148:151], v[248:251], v[112:127]
	v_add_f32_e32 v215, v215, v152
	v_add_f32_e32 v217, v217, v168
	v_mfma_f32_32x32x16_bf16 v[96:111], v[148:151], v[252:255], v[96:111]
	v_add_f32_e32 v215, v215, v153
	v_add_f32_e32 v217, v217, v169
	v_add_f32_e32 v215, v215, v154
	s_waitcnt lgkmcnt(4)
	v_mfma_f32_32x32x16_bf16 v[64:79], v[164:167], v[248:251], v[64:79]
	v_add_f32_e32 v217, v217, v170
	v_add_f32_e32 v215, v215, v155
	v_mfma_f32_32x32x16_bf16 v[80:95], v[164:167], v[252:255], v[80:95]
	v_add_f32_e32 v217, v217, v171
	v_add_f32_e32 v215, v215, v156
	v_add_f32_e32 v217, v217, v172
	s_waitcnt lgkmcnt(2)
	v_mfma_f32_32x32x16_bf16 v[32:47], v[202:205], v[248:251], v[32:47]
	v_add_f32_e32 v215, v215, v157
	v_add_f32_e32 v217, v217, v173
	v_mfma_f32_32x32x16_bf16 v[48:63], v[202:205], v[252:255], v[48:63]
	v_add_f32_e32 v215, v215, v158
	v_add_f32_e32 v217, v217, v174
	v_add_f32_e32 v215, v215, v159
	s_waitcnt lgkmcnt(0)
	v_mfma_f32_32x32x16_bf16 v[0:15], v[244:247], v[248:251], v[0:15]
	v_add_f32_e32 v217, v217, v175
	v_add_f32_e32 v197, v197, v215
	v_mfma_f32_32x32x16_bf16 v[16:31], v[244:247], v[252:255], v[16:31]
	v_add_f32_e32 v196, v196, v217
	s_cmp_gt_i32 s78, s84
	s_cbranch_scc1 .LBB0_778
.LBB0_792:
	ds_read_b128 v[160:163], v237 offset:16384
	ds_read_b128 v[164:167], v189
	ds_read_b128 v[202:205], v235 offset:16384
	ds_read_b128 v[244:247], v189 offset:4096
	ds_read_b128 v[248:251], v236 offset:16384
	ds_read_b128 v[252:255], v189 offset:1024
	s_cmp_lg_u32 s39, s40
	s_waitcnt lgkmcnt(4)
	v_mfma_f32_32x32x16_bf16 v[144:159], v[160:163], v[164:167], v[128:143]
	s_waitcnt lgkmcnt(2)
	v_mfma_f32_32x32x16_bf16 v[160:175], v[202:205], v[244:247], v[128:143]
	ds_read_b128 v[202:205], v234 offset:16384
	ds_read_b128 v[244:247], v189 offset:5120
	v_add_u32_e32 v215, s40, v185
	v_add_u32_e32 v215, 0x80, v215
	v_cvt_f32_i32_e32 v215, v215
	v_add_f32_e32 v227, 0x41000000, v199
	v_mul_f32_e32 v200, v184, v215
	v_add_f32_e32 v215, 0x41000000, v201
	s_waitcnt lgkmcnt(2)
	v_mfma_f32_32x32x16_bf16 v[144:159], v[248:251], v[252:255], v[144:159]
	ds_read_b128 v[248:251], v241 offset:16384
	ds_read_b128 v[252:255], v189 offset:2048
	s_waitcnt lgkmcnt(2)
	v_mfma_f32_32x32x16_bf16 v[160:175], v[202:205], v[244:247], v[160:175]
	ds_read_b128 v[202:205], v239 offset:16384
	ds_read_b128 v[244:247], v189 offset:6144
	s_waitcnt lgkmcnt(2)
	v_mfma_f32_32x32x16_bf16 v[144:159], v[248:251], v[252:255], v[144:159]
	ds_read_b128 v[248:251], v240 offset:16384
	ds_read_b128 v[252:255], v189 offset:3072
	s_waitcnt lgkmcnt(2)
	v_mfma_f32_32x32x16_bf16 v[160:175], v[202:205], v[244:247], v[160:175]
	ds_read_b128 v[202:205], v238 offset:16384
	ds_read_b128 v[244:247], v189 offset:7168
	s_waitcnt lgkmcnt(2)
	v_mfma_f32_32x32x16_bf16 v[144:159], v[248:251], v[252:255], v[144:159]
	s_waitcnt lgkmcnt(0)
	v_mfma_f32_32x32x16_bf16 v[160:175], v[202:205], v[244:247], v[160:175]
	ds_read_b64_tr_b16 v[202:203], v216 offset:16384
	ds_read_b64_tr_b16 v[204:205], v218 offset:16384
	ds_read_b64_tr_b16 v[244:245], v220 offset:16384
	ds_read_b64_tr_b16 v[246:247], v222 offset:16384
	ds_read_b64_tr_b16 v[248:249], v224 offset:16384
	ds_read_b64_tr_b16 v[250:251], v226 offset:16384
	ds_read_b64_tr_b16 v[252:253], v228 offset:16384
	ds_read_b64_tr_b16 v[254:255], v230 offset:16384
	s_cbranch_scc0 .Lat4_diag
.Lat4_go:
	v_sub_f32_e32 v180, v200, v199
	v_sub_f32_e32 v198, v200, v201
	s_nop 0
	v_max3_f32 v217, v144, v145, v146
	v_max3_f32 v219, v160, v161, v162
	v_max3_f32 v221, v147, v148, v149
	v_max3_f32 v225, v163, v164, v165
	v_max3_f32 v223, v150, v151, v152
	v_max3_f32 v229, v166, v167, v168
	v_add_f32_e32 v144, v144, v180
	v_add_f32_e32 v160, v160, v198
	v_max3_f32 v217, v217, v221, v223
	v_exp_f32_e32 v144, v144
	v_exp_f32_e32 v160, v160
	v_max3_f32 v219, v219, v225, v229
	v_add_f32_e32 v145, v145, v180
	v_add_f32_e32 v161, v161, v198
	v_max3_f32 v221, v153, v154, v155
	v_exp_f32_e32 v145, v145
	v_exp_f32_e32 v161, v161
	v_max3_f32 v225, v169, v170, v171
	v_add_f32_e32 v146, v146, v180
	v_add_f32_e32 v162, v162, v198
	v_max3_f32 v223, v156, v157, v158
	v_exp_f32_e32 v146, v146
	v_exp_f32_e32 v162, v162
	v_max3_f32 v229, v172, v173, v174
	v_add_f32_e32 v147, v147, v180
	v_add_f32_e32 v163, v163, v198
	v_max3_f32 v221, v221, v223, v159
	v_exp_f32_e32 v147, v147
	v_exp_f32_e32 v163, v163
	v_max3_f32 v225, v225, v229, v175
	v_add_f32_e32 v148, v148, v180
	v_add_f32_e32 v164, v164, v198
	v_max_f32_e32 v217, v217, v221
	v_exp_f32_e32 v148, v148
	v_exp_f32_e32 v164, v164
	v_max_f32_e32 v219, v219, v225
	v_add_f32_e32 v149, v149, v180
	v_add_f32_e32 v165, v165, v198
	v_add_f32_e32 v221, v200, v217
	v_exp_f32_e32 v149, v149
	v_exp_f32_e32 v165, v165
	v_add_f32_e32 v225, v200, v219
	v_add_f32_e32 v150, v150, v180
	v_add_f32_e32 v166, v166, v198
	v_cmp_gt_f32_e32 vcc, v221, v227
	v_exp_f32_e32 v150, v150
	v_exp_f32_e32 v166, v166
	v_cmp_gt_f32_e64 s[0:1], v225, v215
	v_add_f32_e32 v151, v151, v180
	v_add_f32_e32 v167, v167, v198
	v_exp_f32_e32 v151, v151
	v_exp_f32_e32 v167, v167
	v_add_f32_e32 v215, v144, v145
	v_add_f32_e32 v217, v160, v161
	v_add_f32_e32 v215, v215, v146
	v_add_f32_e32 v217, v217, v162
	v_add_f32_e32 v215, v215, v147
	v_add_f32_e32 v217, v217, v163
	v_add_f32_e32 v215, v215, v148
	v_add_f32_e32 v217, v217, v164
	v_add_f32_e32 v215, v215, v149
	v_add_f32_e32 v217, v217, v165
	v_add_f32_e32 v215, v215, v150
	v_add_f32_e32 v217, v217, v166
	v_add_f32_e32 v215, v215, v151
	v_add_f32_e32 v217, v217, v167
	v_cvt_pk_bf16_f32 v144, v144, v145
	v_cvt_pk_bf16_f32 v160, v160, v161
	v_cvt_pk_bf16_f32 v145, v146, v147
	v_cvt_pk_bf16_f32 v161, v162, v163
	v_cvt_pk_bf16_f32 v146, v148, v149
	v_cvt_pk_bf16_f32 v162, v164, v165
	v_cvt_pk_bf16_f32 v147, v150, v151
	v_cvt_pk_bf16_f32 v163, v166, v167
	ds_read_b64_tr_b16 v[148:149], v216 offset:20480
	ds_read_b64_tr_b16 v[150:151], v218 offset:20480
	ds_read_b64_tr_b16 v[164:165], v220 offset:20480
	ds_read_b64_tr_b16 v[166:167], v222 offset:20480
	s_or_b64 vcc, vcc, s[0:1]
	s_cbranch_vccnz .Lat4_redo
	s_waitcnt lgkmcnt(4)
	v_mfma_f32_32x32x16_bf16 v[112:127], v[202:205], v[144:147], v[112:127]
	v_add_f32_e32 v152, v152, v180
	v_add_f32_e32 v168, v168, v198
	v_exp_f32_e32 v152, v152
	v_exp_f32_e32 v168, v168
	v_mfma_f32_32x32x16_bf16 v[96:111], v[202:205], v[160:163], v[96:111]
	v_add_f32_e32 v153, v153, v180
	v_add_f32_e32 v169, v169, v198
	v_exp_f32_e32 v153, v153
	v_exp_f32_e32 v169, v169
	ds_read_b64_tr_b16 v[202:203], v224 offset:20480
	ds_read_b64_tr_b16 v[204:205], v226 offset:20480
	v_mfma_f32_32x32x16_bf16 v[64:79], v[244:247], v[144:147], v[64:79]
	v_add_f32_e32 v154, v154, v180
	v_add_f32_e32 v170, v170, v198
	v_exp_f32_e32 v154, v154
	v_exp_f32_e32 v170, v170
	v_mfma_f32_32x32x16_bf16 v[80:95], v[244:247], v[160:163], v[80:95]
	v_add_f32_e32 v155, v155, v180
	v_add_f32_e32 v171, v171, v198
	v_exp_f32_e32 v155, v155
	v_exp_f32_e32 v171, v171
	ds_read_b64_tr_b16 v[244:245], v228 offset:20480
	ds_read_b64_tr_b16 v[246:247], v230 offset:20480
	v_mfma_f32_32x32x16_bf16 v[32:47], v[248:251], v[144:147], v[32:47]
	v_add_f32_e32 v156, v156, v180
	v_add_f32_e32 v172, v172, v198
	v_exp_f32_e32 v156, v156
	v_exp_f32_e32 v172, v172
	v_mfma_f32_32x32x16_bf16 v[48:63], v[248:251], v[160:163], v[48:63]
	v_add_f32_e32 v157, v157, v180
	v_add_f32_e32 v173, v173, v198
	v_exp_f32_e32 v157, v157
	v_exp_f32_e32 v173, v173
	v_mfma_f32_32x32x16_bf16 v[0:15], v[252:255], v[144:147], v[0:15]
	v_add_f32_e32 v158, v158, v180
	v_add_f32_e32 v174, v174, v198
	v_exp_f32_e32 v158, v158
	v_exp_f32_e32 v174, v174
	v_mfma_f32_32x32x16_bf16 v[16:31], v[252:255], v[160:163], v[16:31]
	v_add_f32_e32 v159, v159, v180
	v_add_f32_e32 v175, v175, v198
	v_exp_f32_e32 v159, v159
	v_exp_f32_e32 v175, v175
	v_cvt_pk_bf16_f32 v248, v152, v153
	v_cvt_pk_bf16_f32 v252, v168, v169
	v_cvt_pk_bf16_f32 v249, v154, v155
	v_cvt_pk_bf16_f32 v253, v170, v171
	v_cvt_pk_bf16_f32 v250, v156, v157
	v_cvt_pk_bf16_f32 v254, v172, v173
	v_cvt_pk_bf16_f32 v251, v158, v159
	v_cvt_pk_bf16_f32 v255, v174, v175
	s_nop 0
	s_waitcnt lgkmcnt(6)
	v_mfma_f32_32x32x16_bf16 v[112:127], v[148:151], v[248:251], v[112:127]
	v_add_f32_e32 v215, v215, v152
	v_add_f32_e32 v217, v217, v168
	v_mfma_f32_32x32x16_bf16 v[96:111], v[148:151], v[252:255], v[96:111]
	v_add_f32_e32 v215, v215, v153
	v_add_f32_e32 v217, v217, v169
	v_add_f32_e32 v215, v215, v154
	s_waitcnt lgkmcnt(4)
	v_mfma_f32_32x32x16_bf16 v[64:79], v[164:167], v[248:251], v[64:79]
	v_add_f32_e32 v217, v217, v170
	v_add_f32_e32 v215, v215, v155
	v_mfma_f32_32x32x16_bf16 v[80:95], v[164:167], v[252:255], v[80:95]
	v_add_f32_e32 v217, v217, v171
	v_add_f32_e32 v215, v215, v156
	v_add_f32_e32 v217, v217, v172
	s_waitcnt lgkmcnt(2)
	v_mfma_f32_32x32x16_bf16 v[32:47], v[202:205], v[248:251], v[32:47]
	v_add_f32_e32 v215, v215, v157
	v_add_f32_e32 v217, v217, v173
	v_mfma_f32_32x32x16_bf16 v[48:63], v[202:205], v[252:255], v[48:63]
	v_add_f32_e32 v215, v215, v158
	v_add_f32_e32 v217, v217, v174
	v_add_f32_e32 v215, v215, v159
	s_waitcnt lgkmcnt(0)
	v_mfma_f32_32x32x16_bf16 v[0:15], v[244:247], v[248:251], v[0:15]
	v_add_f32_e32 v217, v217, v175
	v_add_f32_e32 v197, v197, v215
	v_mfma_f32_32x32x16_bf16 v[16:31], v[244:247], v[252:255], v[16:31]
	v_add_f32_e32 v196, v196, v217
	s_add_i32 s0, s41, 2
	s_cmp_ge_u32 s0, s85
	s_cbranch_scc1 .LBB0_753
	s_branch .LBB0_779

.LBB0_800:
	ds_read_b128 v[160:163], v237 offset:40960
	ds_read_b128 v[164:167], v189
	ds_read_b128 v[202:205], v235 offset:40960
	ds_read_b128 v[244:247], v189 offset:4096
	ds_read_b128 v[248:251], v236 offset:40960
	ds_read_b128 v[252:255], v189 offset:1024
	s_cmp_lg_u32 s65, s40
	s_waitcnt lgkmcnt(4)
	v_mfma_f32_32x32x16_bf16 v[144:159], v[160:163], v[164:167], v[128:143]
	s_waitcnt lgkmcnt(2)
	v_mfma_f32_32x32x16_bf16 v[160:175], v[202:205], v[244:247], v[128:143]
	ds_read_b128 v[202:205], v234 offset:40960
	ds_read_b128 v[244:247], v189 offset:5120
	v_add_u32_e32 v215, s40, v185
	v_add_u32_e32 v215, 0x60, v215
	v_cvt_f32_i32_e32 v215, v215
	v_add_f32_e32 v227, 0x41000000, v199
	v_mul_f32_e32 v200, v184, v215
	v_add_f32_e32 v215, 0x41000000, v201
	s_waitcnt lgkmcnt(2)
	v_mfma_f32_32x32x16_bf16 v[144:159], v[248:251], v[252:255], v[144:159]
	ds_read_b128 v[248:251], v241 offset:40960
	ds_read_b128 v[252:255], v189 offset:2048
	s_waitcnt lgkmcnt(2)
	v_mfma_f32_32x32x16_bf16 v[160:175], v[202:205], v[244:247], v[160:175]
	ds_read_b128 v[202:205], v239 offset:40960
	ds_read_b128 v[244:247], v189 offset:6144
	s_waitcnt lgkmcnt(2)
	v_mfma_f32_32x32x16_bf16 v[144:159], v[248:251], v[252:255], v[144:159]
	ds_read_b128 v[248:251], v240 offset:40960
	ds_read_b128 v[252:255], v189 offset:3072
	s_waitcnt lgkmcnt(2)
	v_mfma_f32_32x32x16_bf16 v[160:175], v[202:205], v[244:247], v[160:175]
	ds_read_b128 v[202:205], v238 offset:40960
	ds_read_b128 v[244:247], v189 offset:7168
	s_waitcnt lgkmcnt(2)
	v_mfma_f32_32x32x16_bf16 v[144:159], v[248:251], v[252:255], v[144:159]
	s_waitcnt lgkmcnt(0)
	v_mfma_f32_32x32x16_bf16 v[160:175], v[202:205], v[244:247], v[160:175]
	ds_read_b64_tr_b16 v[202:203], v216 offset:40960
	ds_read_b64_tr_b16 v[204:205], v218 offset:40960
	ds_read_b64_tr_b16 v[244:245], v220 offset:40960
	ds_read_b64_tr_b16 v[246:247], v222 offset:40960
	ds_read_b64_tr_b16 v[248:249], v224 offset:40960
	ds_read_b64_tr_b16 v[250:251], v226 offset:40960
	ds_read_b64_tr_b16 v[252:253], v228 offset:40960
	ds_read_b64_tr_b16 v[254:255], v230 offset:40960
	s_cbranch_scc0 .Lat5_diag
.Lat5_go:
	v_sub_f32_e32 v180, v200, v199
	v_sub_f32_e32 v198, v200, v201
	s_nop 0
	v_max3_f32 v217, v144, v145, v146
	v_max3_f32 v219, v160, v161, v162
	v_max3_f32 v221, v147, v148, v149
	v_max3_f32 v225, v163, v164, v165
	v_max3_f32 v223, v150, v151, v152
	v_max3_f32 v229, v166, v167, v168
	v_add_f32_e32 v144, v144, v180
	v_add_f32_e32 v160, v160, v198
	v_max3_f32 v217, v217, v221, v223
	v_exp_f32_e32 v144, v144
	v_exp_f32_e32 v160, v160
	v_max3_f32 v219, v219, v225, v229
	v_add_f32_e32 v145, v145, v180
	v_add_f32_e32 v161, v161, v198
	v_max3_f32 v221, v153, v154, v155
	v_exp_f32_e32 v145, v145
	v_exp_f32_e32 v161, v161
	v_max3_f32 v225, v169, v170, v171
	v_add_f32_e32 v146, v146, v180
	v_add_f32_e32 v162, v162, v198
	v_max3_f32 v223, v156, v157, v158
	v_exp_f32_e32 v146, v146
	v_exp_f32_e32 v162, v162
	v_max3_f32 v229, v172, v173, v174
	v_add_f32_e32 v147, v147, v180
	v_add_f32_e32 v163, v163, v198
	v_max3_f32 v221, v221, v223, v159
	v_exp_f32_e32 v147, v147
	v_exp_f32_e32 v163, v163
	v_max3_f32 v225, v225, v229, v175
	v_add_f32_e32 v148, v148, v180
	v_add_f32_e32 v164, v164, v198
	v_max_f32_e32 v217, v217, v221
	v_exp_f32_e32 v148, v148
	v_exp_f32_e32 v164, v164
	v_max_f32_e32 v219, v219, v225
	v_add_f32_e32 v149, v149, v180
	v_add_f32_e32 v165, v165, v198
	v_add_f32_e32 v221, v200, v217
	v_exp_f32_e32 v149, v149
	v_exp_f32_e32 v165, v165
	v_add_f32_e32 v225, v200, v219
	v_add_f32_e32 v150, v150, v180
	v_add_f32_e32 v166, v166, v198
	v_cmp_gt_f32_e32 vcc, v221, v227
	v_exp_f32_e32 v150, v150
	v_exp_f32_e32 v166, v166
	v_cmp_gt_f32_e64 s[0:1], v225, v215
	v_add_f32_e32 v151, v151, v180
	v_add_f32_e32 v167, v167, v198
	v_exp_f32_e32 v151, v151
	v_exp_f32_e32 v167, v167
	v_add_f32_e32 v215, v144, v145
	v_add_f32_e32 v217, v160, v161
	v_add_f32_e32 v215, v215, v146
	v_add_f32_e32 v217, v217, v162
	v_add_f32_e32 v215, v215, v147
	v_add_f32_e32 v217, v217, v163
	v_add_f32_e32 v215, v215, v148
	v_add_f32_e32 v217, v217, v164
	v_add_f32_e32 v215, v215, v149
	v_add_f32_e32 v217, v217, v165
	v_add_f32_e32 v215, v215, v150
	v_add_f32_e32 v217, v217, v166
	v_add_f32_e32 v215, v215, v151
	v_add_f32_e32 v217, v217, v167
	v_cvt_pk_bf16_f32 v144, v144, v145
	v_cvt_pk_bf16_f32 v160, v160, v161
	v_cvt_pk_bf16_f32 v145, v146, v147
	v_cvt_pk_bf16_f32 v161, v162, v163
	v_cvt_pk_bf16_f32 v146, v148, v149
	v_cvt_pk_bf16_f32 v162, v164, v165
	v_cvt_pk_bf16_f32 v147, v150, v151
	v_cvt_pk_bf16_f32 v163, v166, v167
	ds_read_b64_tr_b16 v[148:149], v216 offset:45056
	ds_read_b64_tr_b16 v[150:151], v218 offset:45056
	ds_read_b64_tr_b16 v[164:165], v220 offset:45056
	ds_read_b64_tr_b16 v[166:167], v222 offset:45056
	s_or_b64 vcc, vcc, s[0:1]
	s_cbranch_vccnz .Lat5_redo
	s_waitcnt lgkmcnt(4)
	v_mfma_f32_32x32x16_bf16 v[112:127], v[202:205], v[144:147], v[112:127]
	v_add_f32_e32 v152, v152, v180
	v_add_f32_e32 v168, v168, v198
	v_exp_f32_e32 v152, v152
	v_exp_f32_e32 v168, v168
	v_mfma_f32_32x32x16_bf16 v[96:111], v[202:205], v[160:163], v[96:111]
	v_add_f32_e32 v153, v153, v180
	v_add_f32_e32 v169, v169, v198
	v_exp_f32_e32 v153, v153
	v_exp_f32_e32 v169, v169
	ds_read_b64_tr_b16 v[202:203], v224 offset:45056
	ds_read_b64_tr_b16 v[204:205], v226 offset:45056
	v_mfma_f32_32x32x16_bf16 v[64:79], v[244:247], v[144:147], v[64:79]
	v_add_f32_e32 v154, v154, v180
	v_add_f32_e32 v170, v170, v198
	v_exp_f32_e32 v154, v154
	v_exp_f32_e32 v170, v170
	v_mfma_f32_32x32x16_bf16 v[80:95], v[244:247], v[160:163], v[80:95]
	v_add_f32_e32 v155, v155, v180
	v_add_f32_e32 v171, v171, v198
	v_exp_f32_e32 v155, v155
	v_exp_f32_e32 v171, v171
	ds_read_b64_tr_b16 v[244:245], v228 offset:45056
	ds_read_b64_tr_b16 v[246:247], v230 offset:45056
	v_mfma_f32_32x32x16_bf16 v[32:47], v[248:251], v[144:147], v[32:47]
	v_add_f32_e32 v156, v156, v180
	v_add_f32_e32 v172, v172, v198
	v_exp_f32_e32 v156, v156
	v_exp_f32_e32 v172, v172
	v_mfma_f32_32x32x16_bf16 v[48:63], v[248:251], v[160:163], v[48:63]
	v_add_f32_e32 v157, v157, v180
	v_add_f32_e32 v173, v173, v198
	v_exp_f32_e32 v157, v157
	v_exp_f32_e32 v173, v173
	v_mfma_f32_32x32x16_bf16 v[0:15], v[252:255], v[144:147], v[0:15]
	v_add_f32_e32 v158, v158, v180
	v_add_f32_e32 v174, v174, v198
	v_exp_f32_e32 v158, v158
	v_exp_f32_e32 v174, v174
	v_mfma_f32_32x32x16_bf16 v[16:31], v[252:255], v[160:163], v[16:31]
	v_add_f32_e32 v159, v159, v180
	v_add_f32_e32 v175, v175, v198
	v_exp_f32_e32 v159, v159
	v_exp_f32_e32 v175, v175
	v_cvt_pk_bf16_f32 v248, v152, v153
	v_cvt_pk_bf16_f32 v252, v168, v169
	v_cvt_pk_bf16_f32 v249, v154, v155
	v_cvt_pk_bf16_f32 v253, v170, v171
	v_cvt_pk_bf16_f32 v250, v156, v157
	v_cvt_pk_bf16_f32 v254, v172, v173
	v_cvt_pk_bf16_f32 v251, v158, v159
	v_cvt_pk_bf16_f32 v255, v174, v175
	s_nop 0
	s_waitcnt lgkmcnt(6)
	v_mfma_f32_32x32x16_bf16 v[112:127], v[148:151], v[248:251], v[112:127]
	v_add_f32_e32 v215, v215, v152
	v_add_f32_e32 v217, v217, v168
	v_mfma_f32_32x32x16_bf16 v[96:111], v[148:151], v[252:255], v[96:111]
	v_add_f32_e32 v215, v215, v153
	v_add_f32_e32 v217, v217, v169
	v_add_f32_e32 v215, v215, v154
	s_waitcnt lgkmcnt(4)
	v_mfma_f32_32x32x16_bf16 v[64:79], v[164:167], v[248:251], v[64:79]
	v_add_f32_e32 v217, v217, v170
	v_add_f32_e32 v215, v215, v155
	v_mfma_f32_32x32x16_bf16 v[80:95], v[164:167], v[252:255], v[80:95]
	v_add_f32_e32 v217, v217, v171
	v_add_f32_e32 v215, v215, v156
	v_add_f32_e32 v217, v217, v172
	s_waitcnt lgkmcnt(2)
	v_mfma_f32_32x32x16_bf16 v[32:47], v[202:205], v[248:251], v[32:47]
	v_add_f32_e32 v215, v215, v157
	v_add_f32_e32 v217, v217, v173
	v_mfma_f32_32x32x16_bf16 v[48:63], v[202:205], v[252:255], v[48:63]
	v_add_f32_e32 v215, v215, v158
	v_add_f32_e32 v217, v217, v174
	v_add_f32_e32 v215, v215, v159
	s_waitcnt lgkmcnt(0)
	v_mfma_f32_32x32x16_bf16 v[0:15], v[244:247], v[248:251], v[0:15]
	v_add_f32_e32 v217, v217, v175
	v_add_f32_e32 v197, v197, v215
	v_mfma_f32_32x32x16_bf16 v[16:31], v[244:247], v[252:255], v[16:31]
	v_add_f32_e32 v196, v196, v217
	s_cmp_gt_i32 s78, s84
	s_cbranch_scc1 .LBB0_753
.LBB0_805:
	ds_read_b128 v[160:163], v237 offset:32768
	ds_read_b128 v[164:167], v189
	ds_read_b128 v[202:205], v235 offset:32768
	ds_read_b128 v[244:247], v189 offset:4096
	ds_read_b128 v[248:251], v236 offset:32768
	ds_read_b128 v[252:255], v189 offset:1024
	s_cmp_lg_u32 s97, s40
	s_waitcnt lgkmcnt(4)
	v_mfma_f32_32x32x16_bf16 v[144:159], v[160:163], v[164:167], v[128:143]
	s_waitcnt lgkmcnt(2)
	v_mfma_f32_32x32x16_bf16 v[160:175], v[202:205], v[244:247], v[128:143]
	ds_read_b128 v[202:205], v234 offset:32768
	ds_read_b128 v[244:247], v189 offset:5120
	v_add_u32_e32 v215, s40, v185
	v_add_u32_e32 v215, 0x40, v215
	v_cvt_f32_i32_e32 v215, v215
	v_add_f32_e32 v227, 0x41000000, v199
	v_mul_f32_e32 v200, v184, v215
	v_add_f32_e32 v215, 0x41000000, v201
	s_waitcnt lgkmcnt(2)
	v_mfma_f32_32x32x16_bf16 v[144:159], v[248:251], v[252:255], v[144:159]
	ds_read_b128 v[248:251], v241 offset:32768
	ds_read_b128 v[252:255], v189 offset:2048
	s_waitcnt lgkmcnt(2)
	v_mfma_f32_32x32x16_bf16 v[160:175], v[202:205], v[244:247], v[160:175]
	ds_read_b128 v[202:205], v239 offset:32768
	ds_read_b128 v[244:247], v189 offset:6144
	s_waitcnt lgkmcnt(2)
	v_mfma_f32_32x32x16_bf16 v[144:159], v[248:251], v[252:255], v[144:159]
	ds_read_b128 v[248:251], v240 offset:32768
	ds_read_b128 v[252:255], v189 offset:3072
	s_waitcnt lgkmcnt(2)
	v_mfma_f32_32x32x16_bf16 v[160:175], v[202:205], v[244:247], v[160:175]
	ds_read_b128 v[202:205], v238 offset:32768
	ds_read_b128 v[244:247], v189 offset:7168
	s_waitcnt lgkmcnt(2)
	v_mfma_f32_32x32x16_bf16 v[144:159], v[248:251], v[252:255], v[144:159]
	s_waitcnt lgkmcnt(0)
	v_mfma_f32_32x32x16_bf16 v[160:175], v[202:205], v[244:247], v[160:175]
	ds_read_b64_tr_b16 v[202:203], v216 offset:32768
	ds_read_b64_tr_b16 v[204:205], v218 offset:32768
	ds_read_b64_tr_b16 v[244:245], v220 offset:32768
	ds_read_b64_tr_b16 v[246:247], v222 offset:32768
	ds_read_b64_tr_b16 v[248:249], v224 offset:32768
	ds_read_b64_tr_b16 v[250:251], v226 offset:32768
	ds_read_b64_tr_b16 v[252:253], v228 offset:32768
	ds_read_b64_tr_b16 v[254:255], v230 offset:32768
	s_cbranch_scc0 .Lat6_diag
.Lat6_go:
	v_sub_f32_e32 v180, v200, v199
	v_sub_f32_e32 v198, v200, v201
	s_nop 0
	v_max3_f32 v217, v144, v145, v146
	v_max3_f32 v219, v160, v161, v162
	v_max3_f32 v221, v147, v148, v149
	v_max3_f32 v225, v163, v164, v165
	v_max3_f32 v223, v150, v151, v152
	v_max3_f32 v229, v166, v167, v168
	v_add_f32_e32 v144, v144, v180
	v_add_f32_e32 v160, v160, v198
	v_max3_f32 v217, v217, v221, v223
	v_exp_f32_e32 v144, v144
	v_exp_f32_e32 v160, v160
	v_max3_f32 v219, v219, v225, v229
	v_add_f32_e32 v145, v145, v180
	v_add_f32_e32 v161, v161, v198
	v_max3_f32 v221, v153, v154, v155
	v_exp_f32_e32 v145, v145
	v_exp_f32_e32 v161, v161
	v_max3_f32 v225, v169, v170, v171
	v_add_f32_e32 v146, v146, v180
	v_add_f32_e32 v162, v162, v198
	v_max3_f32 v223, v156, v157, v158
	v_exp_f32_e32 v146, v146
	v_exp_f32_e32 v162, v162
	v_max3_f32 v229, v172, v173, v174
	v_add_f32_e32 v147, v147, v180
	v_add_f32_e32 v163, v163, v198
	v_max3_f32 v221, v221, v223, v159
	v_exp_f32_e32 v147, v147
	v_exp_f32_e32 v163, v163
	v_max3_f32 v225, v225, v229, v175
	v_add_f32_e32 v148, v148, v180
	v_add_f32_e32 v164, v164, v198
	v_max_f32_e32 v217, v217, v221
	v_exp_f32_e32 v148, v148
	v_exp_f32_e32 v164, v164
	v_max_f32_e32 v219, v219, v225
	v_add_f32_e32 v149, v149, v180
	v_add_f32_e32 v165, v165, v198
	v_add_f32_e32 v221, v200, v217
	v_exp_f32_e32 v149, v149
	v_exp_f32_e32 v165, v165
	v_add_f32_e32 v225, v200, v219
	v_add_f32_e32 v150, v150, v180
	v_add_f32_e32 v166, v166, v198
	v_cmp_gt_f32_e32 vcc, v221, v227
	v_exp_f32_e32 v150, v150
	v_exp_f32_e32 v166, v166
	v_cmp_gt_f32_e64 s[0:1], v225, v215
	v_add_f32_e32 v151, v151, v180
	v_add_f32_e32 v167, v167, v198
	v_exp_f32_e32 v151, v151
	v_exp_f32_e32 v167, v167
	v_add_f32_e32 v215, v144, v145
	v_add_f32_e32 v217, v160, v161
	v_add_f32_e32 v215, v215, v146
	v_add_f32_e32 v217, v217, v162
	v_add_f32_e32 v215, v215, v147
	v_add_f32_e32 v217, v217, v163
	v_add_f32_e32 v215, v215, v148
	v_add_f32_e32 v217, v217, v164
	v_add_f32_e32 v215, v215, v149
	v_add_f32_e32 v217, v217, v165
	v_add_f32_e32 v215, v215, v150
	v_add_f32_e32 v217, v217, v166
	v_add_f32_e32 v215, v215, v151
	v_add_f32_e32 v217, v217, v167
	v_cvt_pk_bf16_f32 v144, v144, v145
	v_cvt_pk_bf16_f32 v160, v160, v161
	v_cvt_pk_bf16_f32 v145, v146, v147
	v_cvt_pk_bf16_f32 v161, v162, v163
	v_cvt_pk_bf16_f32 v146, v148, v149
	v_cvt_pk_bf16_f32 v162, v164, v165
	v_cvt_pk_bf16_f32 v147, v150, v151
	v_cvt_pk_bf16_f32 v163, v166, v167
	ds_read_b64_tr_b16 v[148:149], v216 offset:36864
	ds_read_b64_tr_b16 v[150:151], v218 offset:36864
	ds_read_b64_tr_b16 v[164:165], v220 offset:36864
	ds_read_b64_tr_b16 v[166:167], v222 offset:36864
	s_or_b64 vcc, vcc, s[0:1]
	s_cbranch_vccnz .Lat6_redo
	s_waitcnt lgkmcnt(4)
	v_mfma_f32_32x32x16_bf16 v[112:127], v[202:205], v[144:147], v[112:127]
	v_add_f32_e32 v152, v152, v180
	v_add_f32_e32 v168, v168, v198
	v_exp_f32_e32 v152, v152
	v_exp_f32_e32 v168, v168
	v_mfma_f32_32x32x16_bf16 v[96:111], v[202:205], v[160:163], v[96:111]
	v_add_f32_e32 v153, v153, v180
	v_add_f32_e32 v169, v169, v198
	v_exp_f32_e32 v153, v153
	v_exp_f32_e32 v169, v169
	ds_read_b64_tr_b16 v[202:203], v224 offset:36864
	ds_read_b64_tr_b16 v[204:205], v226 offset:36864
	v_mfma_f32_32x32x16_bf16 v[64:79], v[244:247], v[144:147], v[64:79]
	v_add_f32_e32 v154, v154, v180
	v_add_f32_e32 v170, v170, v198
	v_exp_f32_e32 v154, v154
	v_exp_f32_e32 v170, v170
	v_mfma_f32_32x32x16_bf16 v[80:95], v[244:247], v[160:163], v[80:95]
	v_add_f32_e32 v155, v155, v180
	v_add_f32_e32 v171, v171, v198
	v_exp_f32_e32 v155, v155
	v_exp_f32_e32 v171, v171
	ds_read_b64_tr_b16 v[244:245], v228 offset:36864
	ds_read_b64_tr_b16 v[246:247], v230 offset:36864
	v_mfma_f32_32x32x16_bf16 v[32:47], v[248:251], v[144:147], v[32:47]
	v_add_f32_e32 v156, v156, v180
	v_add_f32_e32 v172, v172, v198
	v_exp_f32_e32 v156, v156
	v_exp_f32_e32 v172, v172
	v_mfma_f32_32x32x16_bf16 v[48:63], v[248:251], v[160:163], v[48:63]
	v_add_f32_e32 v157, v157, v180
	v_add_f32_e32 v173, v173, v198
	v_exp_f32_e32 v157, v157
	v_exp_f32_e32 v173, v173
	v_mfma_f32_32x32x16_bf16 v[0:15], v[252:255], v[144:147], v[0:15]
	v_add_f32_e32 v158, v158, v180
	v_add_f32_e32 v174, v174, v198
	v_exp_f32_e32 v158, v158
	v_exp_f32_e32 v174, v174
	v_mfma_f32_32x32x16_bf16 v[16:31], v[252:255], v[160:163], v[16:31]
	v_add_f32_e32 v159, v159, v180
	v_add_f32_e32 v175, v175, v198
	v_exp_f32_e32 v159, v159
	v_exp_f32_e32 v175, v175
	v_cvt_pk_bf16_f32 v248, v152, v153
	v_cvt_pk_bf16_f32 v252, v168, v169
	v_cvt_pk_bf16_f32 v249, v154, v155
	v_cvt_pk_bf16_f32 v253, v170, v171
	v_cvt_pk_bf16_f32 v250, v156, v157
	v_cvt_pk_bf16_f32 v254, v172, v173
	v_cvt_pk_bf16_f32 v251, v158, v159
	v_cvt_pk_bf16_f32 v255, v174, v175
	s_nop 0
	s_waitcnt lgkmcnt(6)
	v_mfma_f32_32x32x16_bf16 v[112:127], v[148:151], v[248:251], v[112:127]
	v_add_f32_e32 v215, v215, v152
	v_add_f32_e32 v217, v217, v168
	v_mfma_f32_32x32x16_bf16 v[96:111], v[148:151], v[252:255], v[96:111]
	v_add_f32_e32 v215, v215, v153
	v_add_f32_e32 v217, v217, v169
	v_add_f32_e32 v215, v215, v154
	s_waitcnt lgkmcnt(4)
	v_mfma_f32_32x32x16_bf16 v[64:79], v[164:167], v[248:251], v[64:79]
	v_add_f32_e32 v217, v217, v170
	v_add_f32_e32 v215, v215, v155
	v_mfma_f32_32x32x16_bf16 v[80:95], v[164:167], v[252:255], v[80:95]
	v_add_f32_e32 v217, v217, v171
	v_add_f32_e32 v215, v215, v156
	v_add_f32_e32 v217, v217, v172
	s_waitcnt lgkmcnt(2)
	v_mfma_f32_32x32x16_bf16 v[32:47], v[202:205], v[248:251], v[32:47]
	v_add_f32_e32 v215, v215, v157
	v_add_f32_e32 v217, v217, v173
	v_mfma_f32_32x32x16_bf16 v[48:63], v[202:205], v[252:255], v[48:63]
	v_add_f32_e32 v215, v215, v158
	v_add_f32_e32 v217, v217, v174
	v_add_f32_e32 v215, v215, v159
	s_waitcnt lgkmcnt(0)
	v_mfma_f32_32x32x16_bf16 v[0:15], v[244:247], v[248:251], v[0:15]
	v_add_f32_e32 v217, v217, v175
	v_add_f32_e32 v197, v197, v215
	v_mfma_f32_32x32x16_bf16 v[16:31], v[244:247], v[252:255], v[16:31]
	v_add_f32_e32 v196, v196, v217
	s_branch .LBB0_753
.Lat1_diag:
	s_nop 2
	v_cndmask_b32_e64 v180, v160, v242, s[2:3]
	v_cndmask_b32_e64 v198, v144, v242, s[2:3]
	v_cndmask_b32_e64 v161, v242, v161, s[4:5]
	v_cndmask_b32_e64 v160, v180, v160, s[4:5]
	v_cndmask_b32_e64 v145, v242, v145, s[4:5]
	v_cndmask_b32_e64 v144, v198, v144, s[4:5]
	v_cndmask_b32_e64 v162, v162, v242, s[6:7]
	v_cndmask_b32_e64 v146, v146, v242, s[6:7]
	v_cndmask_b32_e64 v163, v163, v242, s[8:9]
	v_cndmask_b32_e64 v147, v147, v242, s[8:9]
	v_cndmask_b32_e64 v164, v164, v242, s[10:11]
	v_cndmask_b32_e64 v148, v148, v242, s[10:11]
	v_cndmask_b32_e64 v165, v165, v242, s[12:13]
	v_cndmask_b32_e64 v149, v149, v242, s[12:13]
	v_cndmask_b32_e64 v166, v166, v242, s[14:15]
	v_cndmask_b32_e64 v150, v150, v242, s[14:15]
	v_cndmask_b32_e64 v167, v167, v242, s[16:17]
	v_cndmask_b32_e64 v151, v151, v242, s[16:17]
	v_cndmask_b32_e64 v168, v168, v242, s[18:19]
	v_cndmask_b32_e64 v152, v152, v242, s[18:19]
	v_cndmask_b32_e64 v169, v169, v242, s[20:21]
	v_cndmask_b32_e64 v153, v153, v242, s[20:21]
	v_cndmask_b32_e64 v170, v170, v242, s[22:23]
	v_cndmask_b32_e64 v154, v154, v242, s[22:23]
	v_cndmask_b32_e64 v171, v171, v242, s[24:25]
	v_cndmask_b32_e64 v155, v155, v242, s[24:25]
	v_cndmask_b32_e64 v172, v172, v242, s[26:27]
	v_cndmask_b32_e64 v156, v156, v242, s[26:27]
	v_cndmask_b32_e64 v173, v173, v242, s[28:29]
	v_cndmask_b32_e64 v157, v157, v242, s[28:29]
	v_cndmask_b32_e64 v174, v174, v242, s[30:31]
	v_cndmask_b32_e64 v158, v158, v242, s[30:31]
	v_cndmask_b32_e64 v175, v175, v242, s[34:35]
	v_cndmask_b32_e64 v159, v159, v242, s[34:35]
.Lat1_fix:
	v_max3_f32 v217, v144, v145, v146
	v_max3_f32 v219, v160, v161, v162
	v_max3_f32 v221, v147, v148, v149
	v_max3_f32 v225, v163, v164, v165
	v_max3_f32 v223, v150, v151, v152
	v_max3_f32 v229, v166, v167, v168
	v_max3_f32 v217, v217, v221, v223
	v_max3_f32 v219, v219, v225, v229
	v_max3_f32 v221, v153, v154, v155
	v_max3_f32 v225, v169, v170, v171
	v_max3_f32 v223, v156, v157, v158
	v_max3_f32 v229, v172, v173, v174
	v_max3_f32 v221, v221, v223, v159
	v_max3_f32 v225, v225, v229, v175
	v_max_f32_e32 v217, v217, v221
	v_max_f32_e32 v219, v219, v225
	v_mov_b32_e32 v223, v217
	v_mov_b32_e32 v229, v219
	s_nop 1
	v_permlane32_swap_b32_e32 v217, v223
	v_permlane32_swap_b32_e32 v219, v229
	v_max_f32_e32 v217, v217, v223
	v_max_f32_e32 v219, v219, v229
	v_add_f32_e32 v221, v200, v217
	v_add_f32_e32 v225, v200, v219
	v_max_f32_e32 v217, v199, v221
	v_max_f32_e32 v219, v201, v225
	v_sub_f32_e32 v223, v199, v217
	v_exp_f32_e32 v180, v223
	v_sub_f32_e32 v223, v201, v219
	v_exp_f32_e32 v198, v223
	v_mov_b32_e32 v201, v219
	v_mul_f32_e32 v197, v197, v180
	v_mul_f32_e32 v196, v196, v198
	v_pk_mul_f32 v[112:113], v[112:113], v[180:181] op_sel_hi:[1,0]
	v_pk_mul_f32 v[114:115], v[114:115], v[180:181] op_sel_hi:[1,0]
	v_pk_mul_f32 v[116:117], v[116:117], v[180:181] op_sel_hi:[1,0]
	v_pk_mul_f32 v[118:119], v[118:119], v[180:181] op_sel_hi:[1,0]
	v_pk_mul_f32 v[120:121], v[120:121], v[180:181] op_sel_hi:[1,0]
	v_pk_mul_f32 v[122:123], v[122:123], v[180:181] op_sel_hi:[1,0]
	v_pk_mul_f32 v[124:125], v[124:125], v[180:181] op_sel_hi:[1,0]
	v_pk_mul_f32 v[126:127], v[126:127], v[180:181] op_sel_hi:[1,0]
	v_pk_mul_f32 v[64:65], v[64:65], v[180:181] op_sel_hi:[1,0]
	v_pk_mul_f32 v[66:67], v[66:67], v[180:181] op_sel_hi:[1,0]
	v_pk_mul_f32 v[68:69], v[68:69], v[180:181] op_sel_hi:[1,0]
	v_pk_mul_f32 v[70:71], v[70:71], v[180:181] op_sel_hi:[1,0]
	v_pk_mul_f32 v[72:73], v[72:73], v[180:181] op_sel_hi:[1,0]
	v_pk_mul_f32 v[74:75], v[74:75], v[180:181] op_sel_hi:[1,0]
	v_pk_mul_f32 v[76:77], v[76:77], v[180:181] op_sel_hi:[1,0]
	v_pk_mul_f32 v[78:79], v[78:79], v[180:181] op_sel_hi:[1,0]
	v_pk_mul_f32 v[32:33], v[32:33], v[180:181] op_sel_hi:[1,0]
	v_pk_mul_f32 v[34:35], v[34:35], v[180:181] op_sel_hi:[1,0]
	v_pk_mul_f32 v[36:37], v[36:37], v[180:181] op_sel_hi:[1,0]
	v_pk_mul_f32 v[38:39], v[38:39], v[180:181] op_sel_hi:[1,0]
	v_pk_mul_f32 v[40:41], v[40:41], v[180:181] op_sel_hi:[1,0]
	v_pk_mul_f32 v[42:43], v[42:43], v[180:181] op_sel_hi:[1,0]
	v_pk_mul_f32 v[44:45], v[44:45], v[180:181] op_sel_hi:[1,0]
	v_pk_mul_f32 v[46:47], v[46:47], v[180:181] op_sel_hi:[1,0]
	v_pk_mul_f32 v[0:1], v[0:1], v[180:181] op_sel_hi:[1,0]
	v_pk_mul_f32 v[2:3], v[2:3], v[180:181] op_sel_hi:[1,0]
	v_pk_mul_f32 v[4:5], v[4:5], v[180:181] op_sel_hi:[1,0]
	v_pk_mul_f32 v[6:7], v[6:7], v[180:181] op_sel_hi:[1,0]
	v_pk_mul_f32 v[8:9], v[8:9], v[180:181] op_sel_hi:[1,0]
	v_pk_mul_f32 v[10:11], v[10:11], v[180:181] op_sel_hi:[1,0]
	v_pk_mul_f32 v[12:13], v[12:13], v[180:181] op_sel_hi:[1,0]
	v_pk_mul_f32 v[14:15], v[14:15], v[180:181] op_sel_hi:[1,0]
	v_pk_mul_f32 v[96:97], v[96:97], v[198:199] op_sel_hi:[1,0]
	v_pk_mul_f32 v[98:99], v[98:99], v[198:199] op_sel_hi:[1,0]
	v_pk_mul_f32 v[100:101], v[100:101], v[198:199] op_sel_hi:[1,0]
	v_pk_mul_f32 v[102:103], v[102:103], v[198:199] op_sel_hi:[1,0]
	v_pk_mul_f32 v[104:105], v[104:105], v[198:199] op_sel_hi:[1,0]
	v_pk_mul_f32 v[106:107], v[106:107], v[198:199] op_sel_hi:[1,0]
	v_pk_mul_f32 v[108:109], v[108:109], v[198:199] op_sel_hi:[1,0]
	v_pk_mul_f32 v[110:111], v[110:111], v[198:199] op_sel_hi:[1,0]
	v_pk_mul_f32 v[80:81], v[80:81], v[198:199] op_sel_hi:[1,0]
	v_pk_mul_f32 v[82:83], v[82:83], v[198:199] op_sel_hi:[1,0]
	v_pk_mul_f32 v[84:85], v[84:85], v[198:199] op_sel_hi:[1,0]
	v_pk_mul_f32 v[86:87], v[86:87], v[198:199] op_sel_hi:[1,0]
	v_pk_mul_f32 v[88:89], v[88:89], v[198:199] op_sel_hi:[1,0]
	v_pk_mul_f32 v[90:91], v[90:91], v[198:199] op_sel_hi:[1,0]
	v_pk_mul_f32 v[92:93], v[92:93], v[198:199] op_sel_hi:[1,0]
	v_pk_mul_f32 v[94:95], v[94:95], v[198:199] op_sel_hi:[1,0]
	v_pk_mul_f32 v[48:49], v[48:49], v[198:199] op_sel_hi:[1,0]
	v_pk_mul_f32 v[50:51], v[50:51], v[198:199] op_sel_hi:[1,0]
	v_pk_mul_f32 v[52:53], v[52:53], v[198:199] op_sel_hi:[1,0]
	v_pk_mul_f32 v[54:55], v[54:55], v[198:199] op_sel_hi:[1,0]
	v_pk_mul_f32 v[56:57], v[56:57], v[198:199] op_sel_hi:[1,0]
	v_pk_mul_f32 v[58:59], v[58:59], v[198:199] op_sel_hi:[1,0]
	v_pk_mul_f32 v[60:61], v[60:61], v[198:199] op_sel_hi:[1,0]
	v_pk_mul_f32 v[62:63], v[62:63], v[198:199] op_sel_hi:[1,0]
	v_pk_mul_f32 v[16:17], v[16:17], v[198:199] op_sel_hi:[1,0]
	v_pk_mul_f32 v[18:19], v[18:19], v[198:199] op_sel_hi:[1,0]
	v_pk_mul_f32 v[20:21], v[20:21], v[198:199] op_sel_hi:[1,0]
	v_pk_mul_f32 v[22:23], v[22:23], v[198:199] op_sel_hi:[1,0]
	v_pk_mul_f32 v[24:25], v[24:25], v[198:199] op_sel_hi:[1,0]
	v_pk_mul_f32 v[26:27], v[26:27], v[198:199] op_sel_hi:[1,0]
	v_pk_mul_f32 v[28:29], v[28:29], v[198:199] op_sel_hi:[1,0]
	v_pk_mul_f32 v[30:31], v[30:31], v[198:199] op_sel_hi:[1,0]
	v_mov_b32_e32 v199, v217
	v_add_f32_e32 v227, 0x41000000, v199
	v_add_f32_e32 v215, 0x41000000, v201
	s_branch .Lat1_go
.Lat1_redo:
	s_waitcnt lgkmcnt(0)
	ds_read_b128 v[160:163], v237 offset:8192
	ds_read_b128 v[164:167], v189
	ds_read_b128 v[202:205], v235 offset:8192
	ds_read_b128 v[244:247], v189 offset:4096
	ds_read_b128 v[248:251], v236 offset:8192
	ds_read_b128 v[252:255], v189 offset:1024
	s_waitcnt lgkmcnt(4)
	v_mfma_f32_32x32x16_bf16 v[144:159], v[160:163], v[164:167], v[128:143]
	s_waitcnt lgkmcnt(2)
	v_mfma_f32_32x32x16_bf16 v[160:175], v[202:205], v[244:247], v[128:143]
	ds_read_b128 v[202:205], v234 offset:8192
	ds_read_b128 v[244:247], v189 offset:5120
	s_waitcnt lgkmcnt(2)
	v_mfma_f32_32x32x16_bf16 v[144:159], v[248:251], v[252:255], v[144:159]
	ds_read_b128 v[248:251], v241 offset:8192
	ds_read_b128 v[252:255], v189 offset:2048
	s_waitcnt lgkmcnt(2)
	v_mfma_f32_32x32x16_bf16 v[160:175], v[202:205], v[244:247], v[160:175]
	ds_read_b128 v[202:205], v239 offset:8192
	ds_read_b128 v[244:247], v189 offset:6144
	s_waitcnt lgkmcnt(2)
	v_mfma_f32_32x32x16_bf16 v[144:159], v[248:251], v[252:255], v[144:159]
	ds_read_b128 v[248:251], v240 offset:8192
	ds_read_b128 v[252:255], v189 offset:3072
	s_waitcnt lgkmcnt(2)
	v_mfma_f32_32x32x16_bf16 v[160:175], v[202:205], v[244:247], v[160:175]
	ds_read_b128 v[202:205], v238 offset:8192
	ds_read_b128 v[244:247], v189 offset:7168
	s_waitcnt lgkmcnt(2)
	v_mfma_f32_32x32x16_bf16 v[144:159], v[248:251], v[252:255], v[144:159]
	s_waitcnt lgkmcnt(0)
	v_mfma_f32_32x32x16_bf16 v[160:175], v[202:205], v[244:247], v[160:175]
	ds_read_b64_tr_b16 v[202:203], v216 offset:8192
	ds_read_b64_tr_b16 v[204:205], v218 offset:8192
	ds_read_b64_tr_b16 v[244:245], v220 offset:8192
	ds_read_b64_tr_b16 v[246:247], v222 offset:8192
	ds_read_b64_tr_b16 v[248:249], v224 offset:8192
	ds_read_b64_tr_b16 v[250:251], v226 offset:8192
	ds_read_b64_tr_b16 v[252:253], v228 offset:8192
	ds_read_b64_tr_b16 v[254:255], v230 offset:8192
	s_nop 3
	s_branch .Lat1_fix

.Lat2_redo:
	s_waitcnt lgkmcnt(0)
	ds_read_b128 v[160:163], v237
	ds_read_b128 v[164:167], v189
	ds_read_b128 v[202:205], v235
	ds_read_b128 v[244:247], v189 offset:4096
	ds_read_b128 v[248:251], v236
	ds_read_b128 v[252:255], v189 offset:1024
	s_waitcnt lgkmcnt(4)
	v_mfma_f32_32x32x16_bf16 v[144:159], v[160:163], v[164:167], v[128:143]
	s_waitcnt lgkmcnt(2)
	v_mfma_f32_32x32x16_bf16 v[160:175], v[202:205], v[244:247], v[128:143]
	ds_read_b128 v[202:205], v234
	ds_read_b128 v[244:247], v189 offset:5120
	s_waitcnt lgkmcnt(2)
	v_mfma_f32_32x32x16_bf16 v[144:159], v[248:251], v[252:255], v[144:159]
	ds_read_b128 v[248:251], v241
	ds_read_b128 v[252:255], v189 offset:2048
	s_waitcnt lgkmcnt(2)
	v_mfma_f32_32x32x16_bf16 v[160:175], v[202:205], v[244:247], v[160:175]
	ds_read_b128 v[202:205], v239
	ds_read_b128 v[244:247], v189 offset:6144
	s_waitcnt lgkmcnt(2)
	v_mfma_f32_32x32x16_bf16 v[144:159], v[248:251], v[252:255], v[144:159]
	ds_read_b128 v[248:251], v240
	ds_read_b128 v[252:255], v189 offset:3072
	s_waitcnt lgkmcnt(2)
	v_mfma_f32_32x32x16_bf16 v[160:175], v[202:205], v[244:247], v[160:175]
	ds_read_b128 v[202:205], v238
	ds_read_b128 v[244:247], v189 offset:7168
	s_waitcnt lgkmcnt(2)
	v_mfma_f32_32x32x16_bf16 v[144:159], v[248:251], v[252:255], v[144:159]
	s_waitcnt lgkmcnt(0)
	v_mfma_f32_32x32x16_bf16 v[160:175], v[202:205], v[244:247], v[160:175]
	ds_read_b64_tr_b16 v[202:203], v216
	ds_read_b64_tr_b16 v[204:205], v218
	ds_read_b64_tr_b16 v[244:245], v220
	ds_read_b64_tr_b16 v[246:247], v222
	ds_read_b64_tr_b16 v[248:249], v224
	ds_read_b64_tr_b16 v[250:251], v226
	ds_read_b64_tr_b16 v[252:253], v228
	ds_read_b64_tr_b16 v[254:255], v230
	s_nop 3
	s_branch .Lat2_fix

.Lat3_redo:
	s_waitcnt lgkmcnt(0)
	ds_read_b128 v[160:163], v237 offset:24576
	ds_read_b128 v[164:167], v189
	ds_read_b128 v[202:205], v235 offset:24576
	ds_read_b128 v[244:247], v189 offset:4096
	ds_read_b128 v[248:251], v236 offset:24576
	ds_read_b128 v[252:255], v189 offset:1024
	s_waitcnt lgkmcnt(4)
	v_mfma_f32_32x32x16_bf16 v[144:159], v[160:163], v[164:167], v[128:143]
	s_waitcnt lgkmcnt(2)
	v_mfma_f32_32x32x16_bf16 v[160:175], v[202:205], v[244:247], v[128:143]
	ds_read_b128 v[202:205], v234 offset:24576
	ds_read_b128 v[244:247], v189 offset:5120
	s_waitcnt lgkmcnt(2)
	v_mfma_f32_32x32x16_bf16 v[144:159], v[248:251], v[252:255], v[144:159]
	ds_read_b128 v[248:251], v241 offset:24576
	ds_read_b128 v[252:255], v189 offset:2048
	s_waitcnt lgkmcnt(2)
	v_mfma_f32_32x32x16_bf16 v[160:175], v[202:205], v[244:247], v[160:175]
	ds_read_b128 v[202:205], v239 offset:24576
	ds_read_b128 v[244:247], v189 offset:6144
	s_waitcnt lgkmcnt(2)
	v_mfma_f32_32x32x16_bf16 v[144:159], v[248:251], v[252:255], v[144:159]
	ds_read_b128 v[248:251], v240 offset:24576
	ds_read_b128 v[252:255], v189 offset:3072
	s_waitcnt lgkmcnt(2)
	v_mfma_f32_32x32x16_bf16 v[160:175], v[202:205], v[244:247], v[160:175]
	ds_read_b128 v[202:205], v238 offset:24576
	ds_read_b128 v[244:247], v189 offset:7168
	s_waitcnt lgkmcnt(2)
	v_mfma_f32_32x32x16_bf16 v[144:159], v[248:251], v[252:255], v[144:159]
	s_waitcnt lgkmcnt(0)
	v_mfma_f32_32x32x16_bf16 v[160:175], v[202:205], v[244:247], v[160:175]
	ds_read_b64_tr_b16 v[202:203], v216 offset:24576
	ds_read_b64_tr_b16 v[204:205], v218 offset:24576
	ds_read_b64_tr_b16 v[244:245], v220 offset:24576
	ds_read_b64_tr_b16 v[246:247], v222 offset:24576
	ds_read_b64_tr_b16 v[248:249], v224 offset:24576
	ds_read_b64_tr_b16 v[250:251], v226 offset:24576
	ds_read_b64_tr_b16 v[252:253], v228 offset:24576
	ds_read_b64_tr_b16 v[254:255], v230 offset:24576
	s_nop 3
	s_branch .Lat3_fix

.Lat4_redo:
	s_waitcnt lgkmcnt(0)
	ds_read_b128 v[160:163], v237 offset:16384
	ds_read_b128 v[164:167], v189
	ds_read_b128 v[202:205], v235 offset:16384
	ds_read_b128 v[244:247], v189 offset:4096
	ds_read_b128 v[248:251], v236 offset:16384
	ds_read_b128 v[252:255], v189 offset:1024
	s_waitcnt lgkmcnt(4)
	v_mfma_f32_32x32x16_bf16 v[144:159], v[160:163], v[164:167], v[128:143]
	s_waitcnt lgkmcnt(2)
	v_mfma_f32_32x32x16_bf16 v[160:175], v[202:205], v[244:247], v[128:143]
	ds_read_b128 v[202:205], v234 offset:16384
	ds_read_b128 v[244:247], v189 offset:5120
	s_waitcnt lgkmcnt(2)
	v_mfma_f32_32x32x16_bf16 v[144:159], v[248:251], v[252:255], v[144:159]
	ds_read_b128 v[248:251], v241 offset:16384
	ds_read_b128 v[252:255], v189 offset:2048
	s_waitcnt lgkmcnt(2)
	v_mfma_f32_32x32x16_bf16 v[160:175], v[202:205], v[244:247], v[160:175]
	ds_read_b128 v[202:205], v239 offset:16384
	ds_read_b128 v[244:247], v189 offset:6144
	s_waitcnt lgkmcnt(2)
	v_mfma_f32_32x32x16_bf16 v[144:159], v[248:251], v[252:255], v[144:159]
	ds_read_b128 v[248:251], v240 offset:16384
	ds_read_b128 v[252:255], v189 offset:3072
	s_waitcnt lgkmcnt(2)
	v_mfma_f32_32x32x16_bf16 v[160:175], v[202:205], v[244:247], v[160:175]
	ds_read_b128 v[202:205], v238 offset:16384
	ds_read_b128 v[244:247], v189 offset:7168
	s_waitcnt lgkmcnt(2)
	v_mfma_f32_32x32x16_bf16 v[144:159], v[248:251], v[252:255], v[144:159]
	s_waitcnt lgkmcnt(0)
	v_mfma_f32_32x32x16_bf16 v[160:175], v[202:205], v[244:247], v[160:175]
	ds_read_b64_tr_b16 v[202:203], v216 offset:16384
	ds_read_b64_tr_b16 v[204:205], v218 offset:16384
	ds_read_b64_tr_b16 v[244:245], v220 offset:16384
	ds_read_b64_tr_b16 v[246:247], v222 offset:16384
	ds_read_b64_tr_b16 v[248:249], v224 offset:16384
	ds_read_b64_tr_b16 v[250:251], v226 offset:16384
	ds_read_b64_tr_b16 v[252:253], v228 offset:16384
	ds_read_b64_tr_b16 v[254:255], v230 offset:16384
	s_nop 3
	s_branch .Lat4_fix

.Lat5_redo:
	s_waitcnt lgkmcnt(0)
	ds_read_b128 v[160:163], v237 offset:40960
	ds_read_b128 v[164:167], v189
	ds_read_b128 v[202:205], v235 offset:40960
	ds_read_b128 v[244:247], v189 offset:4096
	ds_read_b128 v[248:251], v236 offset:40960
	ds_read_b128 v[252:255], v189 offset:1024
	s_waitcnt lgkmcnt(4)
	v_mfma_f32_32x32x16_bf16 v[144:159], v[160:163], v[164:167], v[128:143]
	s_waitcnt lgkmcnt(2)
	v_mfma_f32_32x32x16_bf16 v[160:175], v[202:205], v[244:247], v[128:143]
	ds_read_b128 v[202:205], v234 offset:40960
	ds_read_b128 v[244:247], v189 offset:5120
	s_waitcnt lgkmcnt(2)
	v_mfma_f32_32x32x16_bf16 v[144:159], v[248:251], v[252:255], v[144:159]
	ds_read_b128 v[248:251], v241 offset:40960
	ds_read_b128 v[252:255], v189 offset:2048
	s_waitcnt lgkmcnt(2)
	v_mfma_f32_32x32x16_bf16 v[160:175], v[202:205], v[244:247], v[160:175]
	ds_read_b128 v[202:205], v239 offset:40960
	ds_read_b128 v[244:247], v189 offset:6144
	s_waitcnt lgkmcnt(2)
	v_mfma_f32_32x32x16_bf16 v[144:159], v[248:251], v[252:255], v[144:159]
	ds_read_b128 v[248:251], v240 offset:40960
	ds_read_b128 v[252:255], v189 offset:3072
	s_waitcnt lgkmcnt(2)
	v_mfma_f32_32x32x16_bf16 v[160:175], v[202:205], v[244:247], v[160:175]
	ds_read_b128 v[202:205], v238 offset:40960
	ds_read_b128 v[244:247], v189 offset:7168
	s_waitcnt lgkmcnt(2)
	v_mfma_f32_32x32x16_bf16 v[144:159], v[248:251], v[252:255], v[144:159]
	s_waitcnt lgkmcnt(0)
	v_mfma_f32_32x32x16_bf16 v[160:175], v[202:205], v[244:247], v[160:175]
	ds_read_b64_tr_b16 v[202:203], v216 offset:40960
	ds_read_b64_tr_b16 v[204:205], v218 offset:40960
	ds_read_b64_tr_b16 v[244:245], v220 offset:40960
	ds_read_b64_tr_b16 v[246:247], v222 offset:40960
	ds_read_b64_tr_b16 v[248:249], v224 offset:40960
	ds_read_b64_tr_b16 v[250:251], v226 offset:40960
	ds_read_b64_tr_b16 v[252:253], v228 offset:40960
	ds_read_b64_tr_b16 v[254:255], v230 offset:40960
	s_nop 3
	s_branch .Lat5_fix

.Lat6_redo:
	s_waitcnt lgkmcnt(0)
	ds_read_b128 v[160:163], v237 offset:32768
	ds_read_b128 v[164:167], v189
	ds_read_b128 v[202:205], v235 offset:32768
	ds_read_b128 v[244:247], v189 offset:4096
	ds_read_b128 v[248:251], v236 offset:32768
	ds_read_b128 v[252:255], v189 offset:1024
	s_waitcnt lgkmcnt(4)
	v_mfma_f32_32x32x16_bf16 v[144:159], v[160:163], v[164:167], v[128:143]
	s_waitcnt lgkmcnt(2)
	v_mfma_f32_32x32x16_bf16 v[160:175], v[202:205], v[244:247], v[128:143]
	ds_read_b128 v[202:205], v234 offset:32768
	ds_read_b128 v[244:247], v189 offset:5120
	s_waitcnt lgkmcnt(2)
	v_mfma_f32_32x32x16_bf16 v[144:159], v[248:251], v[252:255], v[144:159]
	ds_read_b128 v[248:251], v241 offset:32768
	ds_read_b128 v[252:255], v189 offset:2048
	s_waitcnt lgkmcnt(2)
	v_mfma_f32_32x32x16_bf16 v[160:175], v[202:205], v[244:247], v[160:175]
	ds_read_b128 v[202:205], v239 offset:32768
	ds_read_b128 v[244:247], v189 offset:6144
	s_waitcnt lgkmcnt(2)
	v_mfma_f32_32x32x16_bf16 v[144:159], v[248:251], v[252:255], v[144:159]
	ds_read_b128 v[248:251], v240 offset:32768
	ds_read_b128 v[252:255], v189 offset:3072
	s_waitcnt lgkmcnt(2)
	v_mfma_f32_32x32x16_bf16 v[160:175], v[202:205], v[244:247], v[160:175]
	ds_read_b128 v[202:205], v238 offset:32768
	ds_read_b128 v[244:247], v189 offset:7168
	s_waitcnt lgkmcnt(2)
	v_mfma_f32_32x32x16_bf16 v[144:159], v[248:251], v[252:255], v[144:159]
	s_waitcnt lgkmcnt(0)
	v_mfma_f32_32x32x16_bf16 v[160:175], v[202:205], v[244:247], v[160:175]
	ds_read_b64_tr_b16 v[202:203], v216 offset:32768
	ds_read_b64_tr_b16 v[204:205], v218 offset:32768
	ds_read_b64_tr_b16 v[244:245], v220 offset:32768
	ds_read_b64_tr_b16 v[246:247], v222 offset:32768
	ds_read_b64_tr_b16 v[248:249], v224 offset:32768
	ds_read_b64_tr_b16 v[250:251], v226 offset:32768
	ds_read_b64_tr_b16 v[252:253], v228 offset:32768
	ds_read_b64_tr_b16 v[254:255], v230 offset:32768
	s_nop 3
	s_branch .Lat6_fix

.LBB0_828:
	s_andn2_saveexec_b64 s[6:7], s[6:7]
	s_cbranch_execz .LBB0_848
	s_mov_b64 s[6:7], exec
	s_cmp_eq_u32 s101, 0
	s_cbranch_scc0 .LBB0_845
	buffer_wbl2 sc1
	s_waitcnt vmcnt(0)
	v_mbcnt_lo_u32_b32 v0, s6, 0
	v_mbcnt_hi_u32_b32 v0, s7, v0
	v_cmp_eq_u32_e32 vcc, 0, v0
	s_and_saveexec_b64 s[8:9], vcc
	s_cbranch_execz .LBB0_831
	s_bcnt1_i32_b64 s6, s[6:7]
	v_mov_b32_e32 v1, 0x1403000
	v_mov_b32_e32 v2, s6
	global_atomic_add v1, v1, v2, s[60:61] offset:1024 sc0

	.amdhsa_kernel _Z8yoco_fwd4Args
		.amdhsa_group_segment_fixed_size 0
		.amdhsa_private_segment_fixed_size 0
		.amdhsa_kernarg_size 416
		.amdhsa_user_sgpr_count 2
		.amdhsa_user_sgpr_dispatch_ptr 0
		.amdhsa_user_sgpr_queue_ptr 0
		.amdhsa_user_sgpr_kernarg_segment_ptr 1
		.amdhsa_user_sgpr_dispatch_id 0
		.amdhsa_user_sgpr_kernarg_preload_length 0
		.amdhsa_user_sgpr_kernarg_preload_offset 0
		.amdhsa_user_sgpr_private_segment_size 0
		.amdhsa_uses_dynamic_stack 0
		.amdhsa_enable_private_segment 0
		.amdhsa_system_sgpr_workgroup_id_x 1
		.amdhsa_system_sgpr_workgroup_id_y 0
		.amdhsa_system_sgpr_workgroup_id_z 0
		.amdhsa_system_sgpr_workgroup_info 0
		.amdhsa_system_vgpr_workitem_id 2
		.amdhsa_next_free_vgpr 256
		.amdhsa_next_free_sgpr 102
		.amdhsa_accum_offset 256
		.amdhsa_reserve_vcc 1
		.amdhsa_float_round_mode_32 0
		.amdhsa_float_round_mode_16_64 0
		.amdhsa_float_denorm_mode_32 3
		.amdhsa_float_denorm_mode_16_64 3
		.amdhsa_dx10_clamp 1
		.amdhsa_ieee_mode 1
		.amdhsa_fp16_overflow 0
		.amdhsa_tg_split 0
		.amdhsa_exception_fp_ieee_invalid_op 0
		.amdhsa_exception_fp_denorm_src 0
		.amdhsa_exception_fp_ieee_div_zero 0
		.amdhsa_exception_fp_ieee_overflow 0
		.amdhsa_exception_fp_ieee_underflow 0
		.amdhsa_exception_fp_ieee_inexact 0
		.amdhsa_exception_int_div_zero 0
	.end_amdhsa_kernel

amdhsa.kernels:
  - .agpr_count:     0
    .args:
      - .offset:         0
        .size:           160
        .value_kind:     by_value
      - .offset:         160
        .size:           4
        .value_kind:     hidden_block_count_x
      - .offset:         164
        .size:           4
        .value_kind:     hidden_block_count_y
      - .offset:         168
        .size:           4
        .value_kind:     hidden_block_count_z
      - .offset:         172
        .size:           2
        .value_kind:     hidden_group_size_x
      - .offset:         174
        .size:           2
        .value_kind:     hidden_group_size_y
      - .offset:         176
        .size:           2
        .value_kind:     hidden_group_size_z
      - .offset:         178
        .size:           2
        .value_kind:     hidden_remainder_x
      - .offset:         180
        .size:           2
        .value_kind:     hidden_remainder_y
      - .offset:         182
        .size:           2
        .value_kind:     hidden_remainder_z
      - .offset:         200
        .size:           8
        .value_kind:     hidden_global_offset_x
      - .offset:         208
        .size:           8
        .value_kind:     hidden_global_offset_y
      - .offset:         216
        .size:           8
        .value_kind:     hidden_global_offset_z
      - .offset:         224
        .size:           2
        .value_kind:     hidden_grid_dims
      - .offset:         248
        .size:           8
        .value_kind:     hidden_multigrid_sync_arg
      - .offset:         280
        .size:           4
        .value_kind:     hidden_dynamic_lds_size
    .group_segment_fixed_size: 0
    .kernarg_segment_align: 8
    .kernarg_segment_size: 416
    .language:       OpenCL C
    .language_version:
      - 2
      - 0
    .max_flat_workgroup_size: 512
    .name:           _Z8yoco_fwd4Args
    .private_segment_fixed_size: 0
    .sgpr_count:     108
    .sgpr_spill_count: 9
    .symbol:         _Z8yoco_fwd4Args.kd
    .uniform_work_group_size: 1
    .uses_dynamic_stack: false
    .vgpr_count:     256
    .vgpr_spill_count: 0
    .wavefront_size: 64
